# FFN-up sample epilogue: duplicate end-of-unit vmcnt0+barrier dropped; group waits moved below the independent zero-inits
# speedup vs baseline: 1.0017x; 1.0017x over previous
;     __device__ __forceinline__ f32x4 conv4s(const f32x4 c4, const f32x4 pv, int t, const f32x4 w0, const f32x4 w1, const f32x4 w2, const f32x4 bsv) const {
;         f32x4 p1, p2;
; #pragma unroll
;         for (int e = 0; e < 4; ++e) { p1[e] = dpp_f<0x111>(0.f, c4[e]); p2[e] = dpp_f<0x112>(0.f, c4[e]); const float q1 = dpp_f<0x101>(0.f, pv[e]);
;             p1[e] = t == 0 ? q1 : p1[e]; p2[e] = t < 2 ? pv[e] : p2[e]; }
;         f32x4 uu = bsv + w2 * c4 + w1 * p1 + w0 * p2;
;         asm volatile("" : "+v"(uu));
;         return uu;
;     __device__ __forceinline__ void sample(f32x4 (&acc)[2][2][4][2], const Unit& u, int row0t, int wr, int wc, int fr, int fq) const {
;     ...
;             for (int ai = 0; ai < 2; ++ai) {
; #pragma unroll
;                 for (int mp = 0; mp < 4; mp += 4) {
;                     f32x4 pv[4];
; #pragma unroll
;                     for (int k = 0; k < 4; ++k) { pv[k] = (f32x4){0.f, 0.f, 0.f, 0.f}; if (t < 2) pv[k] = *(const f32x4*)((const char*)st + stoff + (unsigned)(((16 * ai + 2 * (mp + k)) * 2 * DFF2 + 4 * n) * 4)); }
; #pragma unroll
;                     for (int k = 0; k < 4; ++k) acc[ai][0][mp + k][n] = conv4s(acc[ai][0][mp + k][n], pv[k], t, w0, w1, w2, bsv);
.Lspp_1:
	s_or_b64 exec, exec, s[100:101]
	s_nop 4
	v_mov_b32_dpp v110, v178 row_shl:1 row_mask:0xf bank_mask:0xf
	v_cmp_eq_u32_e64 s[6:7], 0, v108
	v_cndmask_b32_e64 v100, v109, v178, s[4:5]
	s_nop 0
	v_cndmask_b32_e64 v108, v18, v110, s[6:7]
	s_nop 0
	s_nop 0
	v_mov_b32_dpp v109, v179 row_shl:1 row_mask:0xf bank_mask:0xf bound_ctrl:1
	v_mov_b32_dpp v18, v169 row_shr:1 row_mask:0xf bank_mask:0xf bound_ctrl:1
	v_mov_b32_dpp v110, v169 row_shr:2 row_mask:0xf bank_mask:0xf bound_ctrl:1
	v_cndmask_b32_e64 v109, v18, v109, s[6:7]
	v_cndmask_b32_e64 v101, v110, v179, s[4:5]
	v_mov_b32_dpp v18, v170 row_shr:1 row_mask:0xf bank_mask:0xf bound_ctrl:1
	v_mov_b32_dpp v111, v170 row_shr:2 row_mask:0xf bank_mask:0xf bound_ctrl:1
	v_mov_b32_dpp v110, v180 row_shl:1 row_mask:0xf bank_mask:0xf bound_ctrl:1
	v_cndmask_b32_e64 v110, v18, v110, s[6:7]
	v_cndmask_b32_e64 v102, v111, v180, s[4:5]
	v_mov_b32_dpp v18, v171 row_shr:1 row_mask:0xf bank_mask:0xf bound_ctrl:1
	v_mov_b32_dpp v112, v171 row_shr:2 row_mask:0xf bank_mask:0xf bound_ctrl:1
	v_mov_b32_dpp v111, v181 row_shl:1 row_mask:0xf bank_mask:0xf bound_ctrl:1
	v_pk_fma_f32 v[114:115], v[168:169], v[156:157], v[160:161]
	v_cndmask_b32_e64 v111, v18, v111, s[6:7]
	v_cndmask_b32_e64 v103, v112, v181, s[4:5]
	v_pk_fma_f32 v[112:113], v[170:171], v[158:159], v[162:163]
	v_pk_fma_f32 v[108:109], v[152:153], v[108:109], v[114:115]
	v_pk_fma_f32 v[110:111], v[154:155], v[110:111], v[112:113]
	v_pk_fma_f32 v[112:113], v[24:25], v[100:101], v[108:109]
	v_mov_b32_dpp v18, v164 row_shr:1 row_mask:0xf bank_mask:0xf bound_ctrl:1
	v_mov_b32_dpp v101, v164 row_shr:2 row_mask:0xf bank_mask:0xf bound_ctrl:1
	v_mov_b32_dpp v100, v182 row_shl:1 row_mask:0xf bank_mask:0xf bound_ctrl:1
	v_pk_fma_f32 v[114:115], v[26:27], v[102:103], v[110:111]
	v_cndmask_b32_e64 v100, v18, v100, s[6:7]
	v_cndmask_b32_e64 v36, v101, v182, s[4:5]
	v_mov_b32_dpp v18, v165 row_shr:1 row_mask:0xf bank_mask:0xf bound_ctrl:1
	v_mov_b32_dpp v102, v165 row_shr:2 row_mask:0xf bank_mask:0xf bound_ctrl:1
	v_mov_b32_dpp v101, v183 row_shl:1 row_mask:0xf bank_mask:0xf bound_ctrl:1
	v_cndmask_b32_e64 v101, v18, v101, s[6:7]
	v_cndmask_b32_e64 v37, v102, v183, s[4:5]
	v_mov_b32_dpp v18, v166 row_shr:1 row_mask:0xf bank_mask:0xf bound_ctrl:1
	v_mov_b32_dpp v103, v166 row_shr:2 row_mask:0xf bank_mask:0xf bound_ctrl:1
	v_mov_b32_dpp v102, v184 row_shl:1 row_mask:0xf bank_mask:0xf bound_ctrl:1
	v_cndmask_b32_e64 v102, v18, v102, s[6:7]
	v_cndmask_b32_e64 v38, v103, v184, s[4:5]
	v_mov_b32_dpp v18, v167 row_shr:1 row_mask:0xf bank_mask:0xf bound_ctrl:1
	v_mov_b32_dpp v108, v167 row_shr:2 row_mask:0xf bank_mask:0xf bound_ctrl:1
	v_mov_b32_dpp v103, v185 row_shl:1 row_mask:0xf bank_mask:0xf bound_ctrl:1
	v_pk_fma_f32 v[110:111], v[164:165], v[156:157], v[160:161]
	v_cndmask_b32_e64 v103, v18, v103, s[6:7]
	v_cndmask_b32_e64 v39, v108, v185, s[4:5]
	v_pk_fma_f32 v[108:109], v[166:167], v[158:159], v[162:163]
	v_pk_fma_f32 v[100:101], v[152:153], v[100:101], v[110:111]
	v_pk_fma_f32 v[102:103], v[154:155], v[102:103], v[108:109]
	v_pk_fma_f32 v[108:109], v[24:25], v[36:37], v[100:101]
	v_mov_b32_dpp v18, v104 row_shr:1 row_mask:0xf bank_mask:0xf bound_ctrl:1
	v_mov_b32_dpp v37, v104 row_shr:2 row_mask:0xf bank_mask:0xf bound_ctrl:1
	v_mov_b32_dpp v36, v186 row_shl:1 row_mask:0xf bank_mask:0xf bound_ctrl:1
	v_pk_fma_f32 v[110:111], v[26:27], v[38:39], v[102:103]
	v_cndmask_b32_e64 v36, v18, v36, s[6:7]
	v_cndmask_b32_e64 v38, v37, v186, s[4:5]
	v_mov_b32_dpp v18, v105 row_shr:1 row_mask:0xf bank_mask:0xf bound_ctrl:1
	v_mov_b32_dpp v39, v105 row_shr:2 row_mask:0xf bank_mask:0xf bound_ctrl:1
	v_mov_b32_dpp v37, v187 row_shl:1 row_mask:0xf bank_mask:0xf bound_ctrl:1
	v_cndmask_b32_e64 v37, v18, v37, s[6:7]
	v_cndmask_b32_e64 v39, v39, v187, s[4:5]
	v_mov_b32_dpp v18, v106 row_shr:1 row_mask:0xf bank_mask:0xf bound_ctrl:1
	v_mov_b32_dpp v41, v106 row_shr:2 row_mask:0xf bank_mask:0xf bound_ctrl:1
	v_mov_b32_dpp v40, v188 row_shl:1 row_mask:0xf bank_mask:0xf bound_ctrl:1
	v_cndmask_b32_e64 v40, v18, v40, s[6:7]
	v_cndmask_b32_e64 v42, v41, v188, s[4:5]
	v_pk_fma_f32 v[102:103], v[104:105], v[156:157], v[160:161]
	v_mov_b32_dpp v18, v107 row_shr:1 row_mask:0xf bank_mask:0xf bound_ctrl:1
	v_mov_b32_dpp v41, v189 row_shl:1 row_mask:0xf bank_mask:0xf bound_ctrl:1
	v_pk_fma_f32 v[36:37], v[152:153], v[36:37], v[102:103]
	v_cndmask_b32_e64 v41, v18, v41, s[6:7]
	v_pk_fma_f32 v[104:105], v[24:25], v[38:39], v[36:37]
	v_mov_b32_dpp v18, v136 row_shr:1 row_mask:0xf bank_mask:0xf bound_ctrl:1
	v_mov_b32_dpp v37, v136 row_shr:2 row_mask:0xf bank_mask:0xf bound_ctrl:1
	v_mov_b32_dpp v36, v190 row_shl:1 row_mask:0xf bank_mask:0xf bound_ctrl:1
	v_cndmask_b32_e64 v36, v18, v36, s[6:7]
	v_cndmask_b32_e64 v28, v37, v190, s[4:5]
	v_mov_b32_dpp v100, v107 row_shr:2 row_mask:0xf bank_mask:0xf bound_ctrl:1
	v_mov_b32_dpp v18, v137 row_shr:1 row_mask:0xf bank_mask:0xf bound_ctrl:1
	v_mov_b32_dpp v38, v137 row_shr:2 row_mask:0xf bank_mask:0xf bound_ctrl:1
	v_mov_b32_dpp v37, v191 row_shl:1 row_mask:0xf bank_mask:0xf bound_ctrl:1
	v_cndmask_b32_e64 v43, v100, v189, s[4:5]
	v_pk_fma_f32 v[100:101], v[106:107], v[158:159], v[162:163]
	v_cndmask_b32_e64 v37, v18, v37, s[6:7]
	v_cndmask_b32_e64 v29, v38, v191, s[4:5]
	v_pk_fma_f32 v[40:41], v[154:155], v[40:41], v[100:101]
	v_mov_b32_dpp v18, v138 row_shr:1 row_mask:0xf bank_mask:0xf bound_ctrl:1
	v_mov_b32_dpp v39, v138 row_shr:2 row_mask:0xf bank_mask:0xf bound_ctrl:1
	v_mov_b32_dpp v38, v192 row_shl:1 row_mask:0xf bank_mask:0xf bound_ctrl:1
	v_pk_fma_f32 v[106:107], v[26:27], v[42:43], v[40:41]
	v_cndmask_b32_e64 v38, v18, v38, s[6:7]
;     __device__ __forceinline__ void sample(f32x4 (&acc)[2][2][4][2], const Unit& u, int row0t, int wr, int wc, int fr, int fq) const {
;     ...
;             for (int ai = 0; ai < 2; ++ai) {
; #pragma unroll
;                 for (int mp = 0; mp < 4; mp += 4) {
;                     f32x4 pv[4];
; #pragma unroll
;                     for (int k = 0; k < 4; ++k) { pv[k] = (f32x4){0.f, 0.f, 0.f, 0.f}; if (t < 2) pv[k] = *(const f32x4*)((const char*)st + stoff + (unsigned)(((16 * ai + 2 * (mp + k)) * 2 * DFF2 + 4 * n) * 4)); }
; #pragma unroll
;                     for (int k = 0; k < 4; ++k) acc[ai][0][mp + k][n] = conv4s(acc[ai][0][mp + k][n], pv[k], t, w0, w1, w2, bsv);
	v_cndmask_b32_e64 v30, v39, v192, s[4:5]
	v_mov_b32_dpp v18, v139 row_shr:1 row_mask:0xf bank_mask:0xf bound_ctrl:1
	v_mov_b32_dpp v40, v139 row_shr:2 row_mask:0xf bank_mask:0xf bound_ctrl:1
	v_mov_b32_dpp v39, v193 row_shl:1 row_mask:0xf bank_mask:0xf bound_ctrl:1
	v_cndmask_b32_e64 v39, v18, v39, s[6:7]
	v_cndmask_b32_e64 v31, v40, v193, s[4:5]
	v_pk_fma_f32 v[40:41], v[138:139], v[158:159], v[162:163]
	v_pk_fma_f32 v[42:43], v[136:137], v[156:157], v[160:161]
	v_pk_fma_f32 v[38:39], v[154:155], v[38:39], v[40:41]
	v_pk_fma_f32 v[36:37], v[152:153], v[36:37], v[42:43]
	v_pk_fma_f32 v[102:103], v[26:27], v[30:31], v[38:39]
	v_pk_fma_f32 v[100:101], v[24:25], v[28:29], v[36:37]
	s_nop 0
	v_mov_b32_e32 v28, 0
	v_mov_b32_e32 v36, 0
	v_mov_b32_e32 v37, 0
	v_mov_b32_e32 v38, 0
	v_mov_b32_e32 v39, 0
	v_mov_b32_e32 v29, 0
	v_mov_b32_e32 v30, 0
	v_mov_b32_e32 v31, 0
	v_mov_b32_e32 v136, 0
	v_mov_b32_e32 v164, 0
	v_mov_b32_e32 v165, 0
	v_mov_b32_e32 v166, 0
	v_mov_b32_e32 v167, 0
	v_mov_b32_e32 v137, 0
	v_mov_b32_e32 v138, 0
	v_mov_b32_e32 v139, 0
	s_nop 0
	s_nop 0
	v_mov_b32_e32 v40, v19
	v_mov_b32_dpp v18, v148 row_shr:1 row_mask:0xf bank_mask:0xf bound_ctrl:1
	v_mov_b32_dpp v41, v148 row_shr:2 row_mask:0xf bank_mask:0xf bound_ctrl:1
	v_mov_b32_e32 v178, 0
	v_mov_b32_e32 v179, 0
	v_mov_b32_e32 v180, 0
	v_mov_b32_e32 v181, 0
	v_mov_b32_e32 v182, 0
	v_mov_b32_e32 v183, 0
	v_mov_b32_e32 v184, 0
	v_mov_b32_e32 v185, 0
	v_mov_b32_e32 v186, 0
	v_mov_b32_e32 v187, 0
	v_mov_b32_e32 v188, 0
	v_mov_b32_e32 v189, 0
	v_mov_b32_e32 v190, 0
	v_mov_b32_e32 v191, 0
	v_mov_b32_e32 v192, 0
	v_mov_b32_e32 v193, 0
	s_waitcnt vmcnt(0)
	s_and_saveexec_b64 s[100:101], s[4:5]
	s_cbranch_execz .Lspp_2
	s_mov_b64 s[98:99], 0x10
	v_lshl_add_u64 v[194:195], v[172:173], 0, s[98:99]
	global_load_dwordx4 v[178:181], v[194:195], off
	s_mov_b64 s[98:99], 0x16010
	v_lshl_add_u64 v[194:195], v[172:173], 0, s[98:99]
	global_load_dwordx4 v[182:185], v[194:195], off
	s_mov_b64 s[98:99], 0x2c010
	v_lshl_add_u64 v[194:195], v[172:173], 0, s[98:99]
	global_load_dwordx4 v[186:189], v[194:195], off
	s_mov_b64 s[98:99], 0x42010
	v_lshl_add_u64 v[194:195], v[172:173], 0, s[98:99]
	global_load_dwordx4 v[190:193], v[194:195], off
.Lspp_2:
	s_or_b64 exec, exec, s[100:101]
	s_nop 4
	v_mov_b32_dpp v40, v204 row_shl:1 row_mask:0xf bank_mask:0xf
	v_cndmask_b32_e64 v40, v18, v40, s[6:7]
	v_cndmask_b32_e64 v36, v41, v204, s[4:5]
	s_nop 0
	s_nop 0
	v_mov_b32_dpp v18, v149 row_shr:1 row_mask:0xf bank_mask:0xf bound_ctrl:1
	v_mov_b32_dpp v42, v149 row_shr:2 row_mask:0xf bank_mask:0xf bound_ctrl:1
	v_mov_b32_dpp v41, v205 row_shl:1 row_mask:0xf bank_mask:0xf bound_ctrl:1
	v_cndmask_b32_e64 v41, v18, v41, s[6:7]
	v_cndmask_b32_e64 v37, v42, v205, s[4:5]
	v_mov_b32_dpp v18, v150 row_shr:1 row_mask:0xf bank_mask:0xf bound_ctrl:1
	v_mov_b32_dpp v43, v150 row_shr:2 row_mask:0xf bank_mask:0xf bound_ctrl:1
	v_mov_b32_dpp v42, v206 row_shl:1 row_mask:0xf bank_mask:0xf bound_ctrl:1
	v_cndmask_b32_e64 v42, v18, v42, s[6:7]
	v_cndmask_b32_e64 v38, v43, v206, s[4:5]
	v_pk_fma_f32 v[148:149], v[148:149], v[156:157], v[160:161]
	v_mov_b32_dpp v18, v151 row_shr:1 row_mask:0xf bank_mask:0xf bound_ctrl:1
	v_mov_b32_dpp v43, v207 row_shl:1 row_mask:0xf bank_mask:0xf bound_ctrl:1
	v_pk_fma_f32 v[40:41], v[152:153], v[40:41], v[148:149]
	v_mov_b32_dpp v168, v151 row_shr:2 row_mask:0xf bank_mask:0xf bound_ctrl:1
	v_cndmask_b32_e64 v43, v18, v43, s[6:7]
	v_pk_fma_f32 v[150:151], v[150:151], v[158:159], v[162:163]
	v_pk_fma_f32 v[40:41], v[24:25], v[36:37], v[40:41]
	v_cndmask_b32_e64 v39, v168, v207, s[4:5]
	v_pk_fma_f32 v[42:43], v[154:155], v[42:43], v[150:151]
	v_mov_b32_dpp v18, v144 row_shr:1 row_mask:0xf bank_mask:0xf bound_ctrl:1
	v_mov_b32_dpp v37, v144 row_shr:2 row_mask:0xf bank_mask:0xf bound_ctrl:1
	v_mov_b32_dpp v36, v208 row_shl:1 row_mask:0xf bank_mask:0xf bound_ctrl:1
	v_pk_fma_f32 v[42:43], v[26:27], v[38:39], v[42:43]
	v_cndmask_b32_e64 v36, v18, v36, s[6:7]
	v_cndmask_b32_e64 v28, v37, v208, s[4:5]
	v_mov_b32_dpp v18, v145 row_shr:1 row_mask:0xf bank_mask:0xf bound_ctrl:1
	v_mov_b32_dpp v38, v145 row_shr:2 row_mask:0xf bank_mask:0xf bound_ctrl:1
	v_mov_b32_dpp v37, v209 row_shl:1 row_mask:0xf bank_mask:0xf bound_ctrl:1
	v_cndmask_b32_e64 v37, v18, v37, s[6:7]
	v_cndmask_b32_e64 v29, v38, v209, s[4:5]
	v_mov_b32_dpp v18, v146 row_shr:1 row_mask:0xf bank_mask:0xf bound_ctrl:1
	v_mov_b32_dpp v39, v146 row_shr:2 row_mask:0xf bank_mask:0xf bound_ctrl:1
	v_mov_b32_dpp v38, v210 row_shl:1 row_mask:0xf bank_mask:0xf bound_ctrl:1
	v_cndmask_b32_e64 v38, v18, v38, s[6:7]
	v_cndmask_b32_e64 v30, v39, v210, s[4:5]
	v_pk_fma_f32 v[144:145], v[144:145], v[156:157], v[160:161]
	v_mov_b32_dpp v18, v147 row_shr:1 row_mask:0xf bank_mask:0xf bound_ctrl:1
	v_mov_b32_dpp v39, v211 row_shl:1 row_mask:0xf bank_mask:0xf bound_ctrl:1
	v_pk_fma_f32 v[36:37], v[152:153], v[36:37], v[144:145]
	v_mov_b32_dpp v148, v147 row_shr:2 row_mask:0xf bank_mask:0xf bound_ctrl:1
	v_cndmask_b32_e64 v39, v18, v39, s[6:7]
	v_pk_fma_f32 v[146:147], v[146:147], v[158:159], v[162:163]
	v_pk_fma_f32 v[36:37], v[24:25], v[28:29], v[36:37]
	v_cndmask_b32_e64 v31, v148, v211, s[4:5]
	v_pk_fma_f32 v[38:39], v[154:155], v[38:39], v[146:147]
	v_mov_b32_dpp v18, v140 row_shr:1 row_mask:0xf bank_mask:0xf bound_ctrl:1
	v_mov_b32_dpp v29, v140 row_shr:2 row_mask:0xf bank_mask:0xf bound_ctrl:1
	v_mov_b32_dpp v28, v212 row_shl:1 row_mask:0xf bank_mask:0xf bound_ctrl:1
	v_pk_fma_f32 v[38:39], v[26:27], v[30:31], v[38:39]
	v_cndmask_b32_e64 v28, v18, v28, s[6:7]
	v_cndmask_b32_e64 v144, v29, v212, s[4:5]
	v_mov_b32_dpp v18, v141 row_shr:1 row_mask:0xf bank_mask:0xf bound_ctrl:1
;     __device__ __forceinline__ void sample(f32x4 (&acc)[2][2][4][2], const Unit& u, int row0t, int wr, int wc, int fr, int fq) const {
;     ...
;             for (int ai = 0; ai < 2; ++ai) {
; #pragma unroll
;                 for (int mp = 0; mp < 4; mp += 4) {
;                     f32x4 pv[4];
; #pragma unroll
;                     for (int k = 0; k < 4; ++k) { pv[k] = (f32x4){0.f, 0.f, 0.f, 0.f}; if (t < 2) pv[k] = *(const f32x4*)((const char*)st + stoff + (unsigned)(((16 * ai + 2 * (mp + k)) * 2 * DFF2 + 4 * n) * 4)); }
; #pragma unroll
;                     for (int k = 0; k < 4; ++k) acc[ai][0][mp + k][n] = conv4s(acc[ai][0][mp + k][n], pv[k], t, w0, w1, w2, bsv);
;     ...
;             if (step != 2) { const unsigned cso = (unsigned)((DFF + ca + 4 * n) * 4);
;                 w0 = *(const f32x4*)((const char*)cw + cso); w1 = *(const f32x4*)((const char*)(cw + DFF2) + cso); w2 = *(const f32x4*)((const char*)(cw + 2 * DFF2) + cso); bsv = *(const f32x4*)((const char*)cb + cso);
;                 wk[0] = w0; wk[1] = w1; wk[2] = w2; wk[3] = bsv; }
;             else { w0 = wk[0]; w1 = wk[1]; w2 = wk[2]; bsv = wk[3]; }
; #pragma unroll
;             for (int mp = 0; mp < 4; mp += 4) {
;             f32x4 pv[4];
; #pragma unroll
;             for (int k = 0; k < 4; ++k) { pv[k] = (f32x4){0.f, 0.f, 0.f, 0.f}; if (t < 2) pv[k] = *(const f32x4*)((const char*)st + stoff + (unsigned)(((16 * ai + 2 * (mp + k)) * 2 * DFF2 + DFF + 4 * n) * 4)); }
	v_mov_b32_dpp v30, v141 row_shr:2 row_mask:0xf bank_mask:0xf bound_ctrl:1
	v_mov_b32_dpp v29, v213 row_shl:1 row_mask:0xf bank_mask:0xf bound_ctrl:1
	v_cndmask_b32_e64 v29, v18, v29, s[6:7]
	v_cndmask_b32_e64 v145, v30, v213, s[4:5]
	v_mov_b32_dpp v18, v142 row_shr:1 row_mask:0xf bank_mask:0xf bound_ctrl:1
	v_mov_b32_dpp v31, v142 row_shr:2 row_mask:0xf bank_mask:0xf bound_ctrl:1
	v_mov_b32_dpp v30, v214 row_shl:1 row_mask:0xf bank_mask:0xf bound_ctrl:1
	v_cndmask_b32_e64 v30, v18, v30, s[6:7]
	v_cndmask_b32_e64 v146, v31, v214, s[4:5]
	v_pk_fma_f32 v[140:141], v[140:141], v[156:157], v[160:161]
	v_mov_b32_dpp v18, v143 row_shr:1 row_mask:0xf bank_mask:0xf bound_ctrl:1
	v_mov_b32_dpp v31, v215 row_shl:1 row_mask:0xf bank_mask:0xf bound_ctrl:1
	v_cndmask_b32_e64 v31, v18, v31, s[6:7]
	v_pk_fma_f32 v[28:29], v[152:153], v[28:29], v[140:141]
	v_mov_b32_dpp v147, v143 row_shr:2 row_mask:0xf bank_mask:0xf bound_ctrl:1
	v_pk_fma_f32 v[142:143], v[142:143], v[158:159], v[162:163]
	v_mov_b32_dpp v18, v128 row_shr:1 row_mask:0xf bank_mask:0xf bound_ctrl:1
	v_mov_b32_dpp v141, v128 row_shr:2 row_mask:0xf bank_mask:0xf bound_ctrl:1
	v_mov_b32_dpp v140, v216 row_shl:1 row_mask:0xf bank_mask:0xf bound_ctrl:1
	v_pk_fma_f32 v[30:31], v[154:155], v[30:31], v[142:143]
	v_cndmask_b32_e64 v140, v18, v140, s[6:7]
	v_cndmask_b32_e64 v136, v141, v216, s[4:5]
	v_mov_b32_dpp v18, v129 row_shr:1 row_mask:0xf bank_mask:0xf bound_ctrl:1
	v_mov_b32_dpp v142, v129 row_shr:2 row_mask:0xf bank_mask:0xf bound_ctrl:1
	v_mov_b32_dpp v141, v217 row_shl:1 row_mask:0xf bank_mask:0xf bound_ctrl:1
	v_cndmask_b32_e64 v141, v18, v141, s[6:7]
	v_cndmask_b32_e64 v137, v142, v217, s[4:5]
	v_mov_b32_dpp v18, v130 row_shr:1 row_mask:0xf bank_mask:0xf bound_ctrl:1
	v_mov_b32_dpp v143, v130 row_shr:2 row_mask:0xf bank_mask:0xf bound_ctrl:1
	v_mov_b32_dpp v142, v218 row_shl:1 row_mask:0xf bank_mask:0xf bound_ctrl:1
	v_cndmask_b32_e64 v142, v18, v142, s[6:7]
	v_cndmask_b32_e64 v138, v143, v218, s[4:5]
	v_pk_fma_f32 v[28:29], v[24:25], v[144:145], v[28:29]
	v_mov_b32_dpp v18, v131 row_shr:1 row_mask:0xf bank_mask:0xf bound_ctrl:1
	v_mov_b32_dpp v143, v219 row_shl:1 row_mask:0xf bank_mask:0xf bound_ctrl:1
	v_cndmask_b32_e64 v143, v18, v143, s[6:7]
	v_mov_b32_dpp v144, v131 row_shr:2 row_mask:0xf bank_mask:0xf bound_ctrl:1
	v_pk_fma_f32 v[130:131], v[130:131], v[158:159], v[162:163]
	v_pk_fma_f32 v[128:129], v[128:129], v[156:157], v[160:161]
	v_cndmask_b32_e64 v147, v147, v215, s[4:5]
	v_cndmask_b32_e64 v139, v144, v219, s[4:5]
	v_pk_fma_f32 v[130:131], v[154:155], v[142:143], v[130:131]
	v_pk_fma_f32 v[128:129], v[152:153], v[140:141], v[128:129]
	v_pk_fma_f32 v[30:31], v[26:27], v[146:147], v[30:31]
	v_pk_fma_f32 v[26:27], v[26:27], v[138:139], v[130:131]
	v_pk_fma_f32 v[24:25], v[24:25], v[136:137], v[128:129]
	s_nop 0
	v_add_u32_e32 v18, 16, v176
	global_load_dwordx4 v[140:143], v18, s[0:1]
	global_load_dwordx4 v[144:147], v18, s[8:9]
	global_load_dwordx4 v[136:139], v18, s[96:97]
	global_load_dwordx4 v[148:151], v18, s[66:67]
	v_mov_b32_e32 v156, 0
	v_mov_b32_e32 v128, 0
	v_mov_b32_e32 v129, 0
	v_mov_b32_e32 v130, 0
	v_mov_b32_e32 v131, 0
	v_mov_b32_e32 v157, 0
	v_mov_b32_e32 v158, 0
	v_mov_b32_e32 v159, 0
	v_mov_b32_e32 v152, 0
	v_mov_b32_e32 v160, 0
	v_mov_b32_e32 v161, 0
	v_mov_b32_e32 v162, 0
	v_mov_b32_e32 v163, 0
	v_mov_b32_e32 v153, 0
	v_mov_b32_e32 v154, 0
	v_mov_b32_e32 v155, 0
	s_nop 0
	s_nop 0
	v_mov_b32_e32 v164, v19
	v_mov_b32_dpp v18, v124 row_shr:1 row_mask:0xf bank_mask:0xf bound_ctrl:1
	v_mov_b32_dpp v165, v124 row_shr:2 row_mask:0xf bank_mask:0xf bound_ctrl:1
	v_mov_b32_e32 v204, 0
	v_mov_b32_e32 v205, 0
	v_mov_b32_e32 v206, 0
	v_mov_b32_e32 v207, 0
	v_mov_b32_e32 v208, 0
	v_mov_b32_e32 v209, 0
	v_mov_b32_e32 v210, 0
	v_mov_b32_e32 v211, 0
	v_mov_b32_e32 v212, 0
	v_mov_b32_e32 v213, 0
	v_mov_b32_e32 v214, 0
	v_mov_b32_e32 v215, 0
	v_mov_b32_e32 v216, 0
	v_mov_b32_e32 v217, 0
	v_mov_b32_e32 v218, 0
	v_mov_b32_e32 v219, 0
	s_waitcnt vmcnt(0)
	s_and_saveexec_b64 s[100:101], s[4:5]
	s_cbranch_execz .Lspp_3
	s_mov_b64 s[98:99], 0xb0010
	v_lshl_add_u64 v[194:195], v[172:173], 0, s[98:99]
	global_load_dwordx4 v[204:207], v[194:195], off
	s_mov_b64 s[98:99], 0xc6010
	v_lshl_add_u64 v[194:195], v[172:173], 0, s[98:99]
	global_load_dwordx4 v[208:211], v[194:195], off
	s_mov_b64 s[98:99], 0xdc010
	v_lshl_add_u64 v[194:195], v[172:173], 0, s[98:99]
	global_load_dwordx4 v[212:215], v[194:195], off
	s_mov_b64 s[98:99], 0xf2010
	v_lshl_add_u64 v[194:195], v[172:173], 0, s[98:99]
	global_load_dwordx4 v[216:219], v[194:195], off
;     __device__ __forceinline__ f32x4 conv4s(const f32x4 c4, const f32x4 pv, int t, const f32x4 w0, const f32x4 w1, const f32x4 w2, const f32x4 bsv) const {
;         f32x4 p1, p2;
; #pragma unroll
;         for (int e = 0; e < 4; ++e) { p1[e] = dpp_f<0x111>(0.f, c4[e]); p2[e] = dpp_f<0x112>(0.f, c4[e]); const float q1 = dpp_f<0x101>(0.f, pv[e]);
;             p1[e] = t == 0 ? q1 : p1[e]; p2[e] = t < 2 ? pv[e] : p2[e]; }
;         f32x4 uu = bsv + w2 * c4 + w1 * p1 + w0 * p2;
;         asm volatile("" : "+v"(uu));
;         return uu;
;     __device__ __forceinline__ void sample(f32x4 (&acc)[2][2][4][2], const Unit& u, int row0t, int wr, int wc, int fr, int fq) const {
;     ...
;             for (int ai = 0; ai < 2; ++ai) {
; #pragma unroll
;                 for (int mp = 0; mp < 4; mp += 4) {
;                     f32x4 pv[4];
; #pragma unroll
;                     for (int k = 0; k < 4; ++k) { pv[k] = (f32x4){0.f, 0.f, 0.f, 0.f}; if (t < 2) pv[k] = *(const f32x4*)((const char*)st + stoff + (unsigned)(((16 * ai + 2 * (mp + k)) * 2 * DFF2 + 4 * n) * 4)); }
; #pragma unroll
;                     for (int k = 0; k < 4; ++k) acc[ai][0][mp + k][n] = conv4s(acc[ai][0][mp + k][n], pv[k], t, w0, w1, w2, bsv);
.Lspp_3:
	s_or_b64 exec, exec, s[100:101]
	s_nop 4
	v_mov_b32_dpp v164, v178 row_shl:1 row_mask:0xf bank_mask:0xf
	v_cndmask_b32_e64 v164, v18, v164, s[6:7]
	v_cndmask_b32_e64 v128, v165, v178, s[4:5]
	s_nop 0
	s_nop 0
	v_mov_b32_dpp v18, v125 row_shr:1 row_mask:0xf bank_mask:0xf bound_ctrl:1
	v_mov_b32_dpp v166, v125 row_shr:2 row_mask:0xf bank_mask:0xf bound_ctrl:1
	v_mov_b32_dpp v165, v179 row_shl:1 row_mask:0xf bank_mask:0xf bound_ctrl:1
	v_cndmask_b32_e64 v165, v18, v165, s[6:7]
	v_cndmask_b32_e64 v129, v166, v179, s[4:5]
	v_mov_b32_dpp v18, v126 row_shr:1 row_mask:0xf bank_mask:0xf bound_ctrl:1
	v_mov_b32_dpp v167, v126 row_shr:2 row_mask:0xf bank_mask:0xf bound_ctrl:1
	v_mov_b32_dpp v166, v180 row_shl:1 row_mask:0xf bank_mask:0xf bound_ctrl:1
	v_cndmask_b32_e64 v166, v18, v166, s[6:7]
	v_cndmask_b32_e64 v130, v167, v180, s[4:5]
	v_pk_fma_f32 v[124:125], v[124:125], v[144:145], v[148:149]
	v_mov_b32_dpp v18, v127 row_shr:1 row_mask:0xf bank_mask:0xf bound_ctrl:1
	v_mov_b32_dpp v167, v181 row_shl:1 row_mask:0xf bank_mask:0xf bound_ctrl:1
	v_pk_fma_f32 v[124:125], v[140:141], v[164:165], v[124:125]
	v_mov_b32_dpp v168, v127 row_shr:2 row_mask:0xf bank_mask:0xf bound_ctrl:1
	v_cndmask_b32_e64 v167, v18, v167, s[6:7]
	v_pk_fma_f32 v[126:127], v[126:127], v[146:147], v[150:151]
	v_pk_fma_f32 v[128:129], v[136:137], v[128:129], v[124:125]
	v_cndmask_b32_e64 v131, v168, v181, s[4:5]
	v_pk_fma_f32 v[126:127], v[142:143], v[166:167], v[126:127]
	v_mov_b32_dpp v18, v120 row_shr:1 row_mask:0xf bank_mask:0xf bound_ctrl:1
	v_mov_b32_dpp v125, v120 row_shr:2 row_mask:0xf bank_mask:0xf bound_ctrl:1
	v_mov_b32_dpp v124, v182 row_shl:1 row_mask:0xf bank_mask:0xf bound_ctrl:1
	v_pk_fma_f32 v[130:131], v[138:139], v[130:131], v[126:127]
	v_cndmask_b32_e64 v124, v18, v124, s[6:7]
	v_cndmask_b32_e64 v156, v125, v182, s[4:5]
	v_mov_b32_dpp v18, v121 row_shr:1 row_mask:0xf bank_mask:0xf bound_ctrl:1
	v_mov_b32_dpp v126, v121 row_shr:2 row_mask:0xf bank_mask:0xf bound_ctrl:1
	v_mov_b32_dpp v125, v183 row_shl:1 row_mask:0xf bank_mask:0xf bound_ctrl:1
	v_cndmask_b32_e64 v125, v18, v125, s[6:7]
	v_cndmask_b32_e64 v157, v126, v183, s[4:5]
	v_mov_b32_dpp v18, v122 row_shr:1 row_mask:0xf bank_mask:0xf bound_ctrl:1
	v_mov_b32_dpp v127, v122 row_shr:2 row_mask:0xf bank_mask:0xf bound_ctrl:1
	v_mov_b32_dpp v126, v184 row_shl:1 row_mask:0xf bank_mask:0xf bound_ctrl:1
	v_cndmask_b32_e64 v126, v18, v126, s[6:7]
	v_cndmask_b32_e64 v158, v127, v184, s[4:5]
	v_pk_fma_f32 v[120:121], v[120:121], v[144:145], v[148:149]
	v_mov_b32_dpp v18, v123 row_shr:1 row_mask:0xf bank_mask:0xf bound_ctrl:1
	v_mov_b32_dpp v127, v185 row_shl:1 row_mask:0xf bank_mask:0xf bound_ctrl:1
	v_pk_fma_f32 v[120:121], v[140:141], v[124:125], v[120:121]
	v_mov_b32_dpp v164, v123 row_shr:2 row_mask:0xf bank_mask:0xf bound_ctrl:1
	v_cndmask_b32_e64 v127, v18, v127, s[6:7]
	v_pk_fma_f32 v[122:123], v[122:123], v[146:147], v[150:151]
	v_pk_fma_f32 v[124:125], v[136:137], v[156:157], v[120:121]
	v_cndmask_b32_e64 v159, v164, v185, s[4:5]
	v_pk_fma_f32 v[122:123], v[142:143], v[126:127], v[122:123]
	v_mov_b32_dpp v18, v116 row_shr:1 row_mask:0xf bank_mask:0xf bound_ctrl:1
	v_mov_b32_dpp v121, v116 row_shr:2 row_mask:0xf bank_mask:0xf bound_ctrl:1
	v_mov_b32_dpp v120, v186 row_shl:1 row_mask:0xf bank_mask:0xf bound_ctrl:1
	v_pk_fma_f32 v[126:127], v[138:139], v[158:159], v[122:123]
	v_cndmask_b32_e64 v120, v18, v120, s[6:7]
	v_cndmask_b32_e64 v156, v121, v186, s[4:5]
	v_mov_b32_dpp v18, v117 row_shr:1 row_mask:0xf bank_mask:0xf bound_ctrl:1
	v_mov_b32_dpp v122, v117 row_shr:2 row_mask:0xf bank_mask:0xf bound_ctrl:1
	v_mov_b32_dpp v121, v187 row_shl:1 row_mask:0xf bank_mask:0xf bound_ctrl:1
	v_cndmask_b32_e64 v121, v18, v121, s[6:7]
	v_cndmask_b32_e64 v157, v122, v187, s[4:5]
	v_mov_b32_dpp v18, v118 row_shr:1 row_mask:0xf bank_mask:0xf bound_ctrl:1
	v_mov_b32_dpp v123, v118 row_shr:2 row_mask:0xf bank_mask:0xf bound_ctrl:1
	v_mov_b32_dpp v122, v188 row_shl:1 row_mask:0xf bank_mask:0xf bound_ctrl:1
	v_cndmask_b32_e64 v122, v18, v122, s[6:7]
	v_cndmask_b32_e64 v158, v123, v188, s[4:5]
	v_pk_fma_f32 v[116:117], v[116:117], v[144:145], v[148:149]
	v_mov_b32_dpp v18, v119 row_shr:1 row_mask:0xf bank_mask:0xf bound_ctrl:1
	v_mov_b32_dpp v123, v189 row_shl:1 row_mask:0xf bank_mask:0xf bound_ctrl:1
	v_pk_fma_f32 v[116:117], v[140:141], v[120:121], v[116:117]
	v_mov_b32_dpp v159, v119 row_shr:2 row_mask:0xf bank_mask:0xf bound_ctrl:1
	v_cndmask_b32_e64 v123, v18, v123, s[6:7]
	v_pk_fma_f32 v[118:119], v[118:119], v[146:147], v[150:151]
	v_pk_fma_f32 v[120:121], v[136:137], v[156:157], v[116:117]
	v_cndmask_b32_e64 v159, v159, v189, s[4:5]
	v_pk_fma_f32 v[118:119], v[142:143], v[122:123], v[118:119]
	v_mov_b32_dpp v18, v72 row_shr:1 row_mask:0xf bank_mask:0xf bound_ctrl:1
	v_mov_b32_dpp v117, v72 row_shr:2 row_mask:0xf bank_mask:0xf bound_ctrl:1
	v_mov_b32_dpp v116, v190 row_shl:1 row_mask:0xf bank_mask:0xf bound_ctrl:1
	v_pk_fma_f32 v[122:123], v[138:139], v[158:159], v[118:119]
	v_cndmask_b32_e64 v116, v18, v116, s[6:7]
	v_cndmask_b32_e64 v152, v117, v190, s[4:5]
	v_mov_b32_dpp v18, v73 row_shr:1 row_mask:0xf bank_mask:0xf bound_ctrl:1
	v_mov_b32_dpp v118, v73 row_shr:2 row_mask:0xf bank_mask:0xf bound_ctrl:1
	v_mov_b32_dpp v117, v191 row_shl:1 row_mask:0xf bank_mask:0xf bound_ctrl:1
	v_cndmask_b32_e64 v117, v18, v117, s[6:7]
	v_cndmask_b32_e64 v153, v118, v191, s[4:5]
	v_mov_b32_dpp v18, v74 row_shr:1 row_mask:0xf bank_mask:0xf bound_ctrl:1
	v_mov_b32_dpp v119, v74 row_shr:2 row_mask:0xf bank_mask:0xf bound_ctrl:1
	v_mov_b32_dpp v118, v192 row_shl:1 row_mask:0xf bank_mask:0xf bound_ctrl:1
;     __device__ __forceinline__ f32x4 conv4s(const f32x4 c4, const f32x4 pv, int t, const f32x4 w0, const f32x4 w1, const f32x4 w2, const f32x4 bsv) const {
;         f32x4 p1, p2;
; #pragma unroll
;         for (int e = 0; e < 4; ++e) { p1[e] = dpp_f<0x111>(0.f, c4[e]); p2[e] = dpp_f<0x112>(0.f, c4[e]); const float q1 = dpp_f<0x101>(0.f, pv[e]);
;             p1[e] = t == 0 ? q1 : p1[e]; p2[e] = t < 2 ? pv[e] : p2[e]; }
;         f32x4 uu = bsv + w2 * c4 + w1 * p1 + w0 * p2;
;         asm volatile("" : "+v"(uu));
;         return uu;
;     __device__ __forceinline__ void sample(f32x4 (&acc)[2][2][4][2], const Unit& u, int row0t, int wr, int wc, int fr, int fq) const {
;     ...
;             for (int ai = 0; ai < 2; ++ai) {
; #pragma unroll
;                 for (int mp = 0; mp < 4; mp += 4) {
;                     f32x4 pv[4];
; #pragma unroll
;                     for (int k = 0; k < 4; ++k) { pv[k] = (f32x4){0.f, 0.f, 0.f, 0.f}; if (t < 2) pv[k] = *(const f32x4*)((const char*)st + stoff + (unsigned)(((16 * ai + 2 * (mp + k)) * 2 * DFF2 + 4 * n) * 4)); }
; #pragma unroll
;                     for (int k = 0; k < 4; ++k) acc[ai][0][mp + k][n] = conv4s(acc[ai][0][mp + k][n], pv[k], t, w0, w1, w2, bsv);
	v_cndmask_b32_e64 v118, v18, v118, s[6:7]
	v_cndmask_b32_e64 v154, v119, v192, s[4:5]
	v_mov_b32_dpp v18, v75 row_shr:1 row_mask:0xf bank_mask:0xf bound_ctrl:1
	v_mov_b32_dpp v119, v193 row_shl:1 row_mask:0xf bank_mask:0xf bound_ctrl:1
	v_mov_b32_dpp v156, v75 row_shr:2 row_mask:0xf bank_mask:0xf bound_ctrl:1
	v_cndmask_b32_e64 v119, v18, v119, s[6:7]
	v_pk_fma_f32 v[74:75], v[74:75], v[146:147], v[150:151]
	v_pk_fma_f32 v[72:73], v[72:73], v[144:145], v[148:149]
	v_cndmask_b32_e64 v155, v156, v193, s[4:5]
	v_pk_fma_f32 v[74:75], v[142:143], v[118:119], v[74:75]
	v_pk_fma_f32 v[72:73], v[140:141], v[116:117], v[72:73]
	v_pk_fma_f32 v[118:119], v[138:139], v[154:155], v[74:75]
	v_pk_fma_f32 v[116:117], v[136:137], v[152:153], v[72:73]
	s_nop 0
	v_mov_b32_e32 v156, 0
	v_mov_b32_e32 v72, 0
	v_mov_b32_e32 v73, 0
	v_mov_b32_e32 v74, 0
	v_mov_b32_e32 v75, 0
	v_mov_b32_e32 v157, 0
	v_mov_b32_e32 v158, 0
	v_mov_b32_e32 v159, 0
	v_mov_b32_e32 v152, 0
	v_mov_b32_e32 v160, 0
	v_mov_b32_e32 v161, 0
	v_mov_b32_e32 v162, 0
	v_mov_b32_e32 v163, 0
	v_mov_b32_e32 v153, 0
	v_mov_b32_e32 v154, 0
	v_mov_b32_e32 v155, 0
	s_nop 0
	s_nop 0
	v_mov_b32_e32 v164, v19
	v_mov_b32_dpp v18, v132 row_shr:1 row_mask:0xf bank_mask:0xf bound_ctrl:1
	v_mov_b32_dpp v165, v132 row_shr:2 row_mask:0xf bank_mask:0xf bound_ctrl:1
	v_mov_b32_e32 v178, 0
	v_mov_b32_e32 v179, 0
	v_mov_b32_e32 v180, 0
	v_mov_b32_e32 v181, 0
	v_mov_b32_e32 v182, 0
	v_mov_b32_e32 v183, 0
	v_mov_b32_e32 v184, 0
	v_mov_b32_e32 v185, 0
	v_mov_b32_e32 v186, 0
	v_mov_b32_e32 v187, 0
	v_mov_b32_e32 v188, 0
	v_mov_b32_e32 v189, 0
	v_mov_b32_e32 v190, 0
	v_mov_b32_e32 v191, 0
	v_mov_b32_e32 v192, 0
	v_mov_b32_e32 v193, 0
	s_waitcnt vmcnt(0)
	s_and_saveexec_b64 s[100:101], s[4:5]
	s_cbranch_execz .Lspp_4
	s_mov_b64 s[98:99], 0x2c00
	v_lshl_add_u64 v[194:195], v[172:173], 0, s[98:99]
	global_load_dwordx4 v[178:181], v[194:195], off
	s_mov_b64 s[98:99], 0x18c00
	v_lshl_add_u64 v[194:195], v[172:173], 0, s[98:99]
	global_load_dwordx4 v[182:185], v[194:195], off
	s_mov_b64 s[98:99], 0x2ec00
	v_lshl_add_u64 v[194:195], v[172:173], 0, s[98:99]
	global_load_dwordx4 v[186:189], v[194:195], off
	s_mov_b64 s[98:99], 0x44c00
	v_lshl_add_u64 v[194:195], v[172:173], 0, s[98:99]
	global_load_dwordx4 v[190:193], v[194:195], off
.Lspp_4:
	s_or_b64 exec, exec, s[100:101]
	s_nop 4
	v_mov_b32_dpp v164, v204 row_shl:1 row_mask:0xf bank_mask:0xf
	v_cndmask_b32_e64 v164, v18, v164, s[6:7]
	v_cndmask_b32_e64 v72, v165, v204, s[4:5]
	s_nop 0
	s_nop 0
	v_mov_b32_dpp v18, v133 row_shr:1 row_mask:0xf bank_mask:0xf bound_ctrl:1
	v_mov_b32_dpp v166, v133 row_shr:2 row_mask:0xf bank_mask:0xf bound_ctrl:1
	v_mov_b32_dpp v165, v205 row_shl:1 row_mask:0xf bank_mask:0xf bound_ctrl:1
	v_cndmask_b32_e64 v165, v18, v165, s[6:7]
	v_cndmask_b32_e64 v73, v166, v205, s[4:5]
	v_mov_b32_dpp v18, v134 row_shr:1 row_mask:0xf bank_mask:0xf bound_ctrl:1
	v_mov_b32_dpp v167, v134 row_shr:2 row_mask:0xf bank_mask:0xf bound_ctrl:1
	v_mov_b32_dpp v166, v206 row_shl:1 row_mask:0xf bank_mask:0xf bound_ctrl:1
	v_cndmask_b32_e64 v166, v18, v166, s[6:7]
	v_cndmask_b32_e64 v74, v167, v206, s[4:5]
	v_pk_fma_f32 v[132:133], v[132:133], v[144:145], v[148:149]
	v_mov_b32_dpp v18, v135 row_shr:1 row_mask:0xf bank_mask:0xf bound_ctrl:1
	v_mov_b32_dpp v167, v207 row_shl:1 row_mask:0xf bank_mask:0xf bound_ctrl:1
	v_pk_fma_f32 v[132:133], v[140:141], v[164:165], v[132:133]
	v_mov_b32_dpp v168, v135 row_shr:2 row_mask:0xf bank_mask:0xf bound_ctrl:1
	v_cndmask_b32_e64 v167, v18, v167, s[6:7]
	v_pk_fma_f32 v[134:135], v[134:135], v[146:147], v[150:151]
	v_pk_fma_f32 v[72:73], v[136:137], v[72:73], v[132:133]
	v_cndmask_b32_e64 v75, v168, v207, s[4:5]
	v_pk_fma_f32 v[134:135], v[142:143], v[166:167], v[134:135]
	v_mov_b32_dpp v18, v76 row_shr:1 row_mask:0xf bank_mask:0xf bound_ctrl:1
	v_mov_b32_dpp v133, v76 row_shr:2 row_mask:0xf bank_mask:0xf bound_ctrl:1
	v_mov_b32_dpp v132, v208 row_shl:1 row_mask:0xf bank_mask:0xf bound_ctrl:1
	v_pk_fma_f32 v[74:75], v[138:139], v[74:75], v[134:135]
	v_cndmask_b32_e64 v132, v18, v132, s[6:7]
	v_cndmask_b32_e64 v134, v133, v208, s[4:5]
	v_mov_b32_dpp v18, v77 row_shr:1 row_mask:0xf bank_mask:0xf bound_ctrl:1
	v_mov_b32_dpp v135, v77 row_shr:2 row_mask:0xf bank_mask:0xf bound_ctrl:1
	v_mov_b32_dpp v133, v209 row_shl:1 row_mask:0xf bank_mask:0xf bound_ctrl:1
	v_cndmask_b32_e64 v133, v18, v133, s[6:7]
	v_cndmask_b32_e64 v135, v135, v209, s[4:5]
	v_mov_b32_dpp v18, v78 row_shr:1 row_mask:0xf bank_mask:0xf bound_ctrl:1
	v_mov_b32_dpp v157, v78 row_shr:2 row_mask:0xf bank_mask:0xf bound_ctrl:1
	v_mov_b32_dpp v156, v210 row_shl:1 row_mask:0xf bank_mask:0xf bound_ctrl:1
	v_cndmask_b32_e64 v156, v18, v156, s[6:7]
	v_cndmask_b32_e64 v158, v157, v210, s[4:5]
	v_pk_fma_f32 v[76:77], v[76:77], v[144:145], v[148:149]
	v_mov_b32_dpp v18, v79 row_shr:1 row_mask:0xf bank_mask:0xf bound_ctrl:1
	v_mov_b32_dpp v157, v211 row_shl:1 row_mask:0xf bank_mask:0xf bound_ctrl:1
	v_cndmask_b32_e64 v157, v18, v157, s[6:7]
	v_pk_fma_f32 v[76:77], v[140:141], v[132:133], v[76:77]
	v_mov_b32_dpp v18, v80 row_shr:1 row_mask:0xf bank_mask:0xf bound_ctrl:1
	v_mov_b32_dpp v133, v80 row_shr:2 row_mask:0xf bank_mask:0xf bound_ctrl:1
	v_mov_b32_dpp v132, v212 row_shl:1 row_mask:0xf bank_mask:0xf bound_ctrl:1
	v_pk_fma_f32 v[76:77], v[136:137], v[134:135], v[76:77]
	v_cndmask_b32_e64 v132, v18, v132, s[6:7]
	v_cndmask_b32_e64 v134, v133, v212, s[4:5]
	v_mov_b32_dpp v164, v79 row_shr:2 row_mask:0xf bank_mask:0xf bound_ctrl:1
	v_pk_fma_f32 v[78:79], v[78:79], v[146:147], v[150:151]
	v_mov_b32_dpp v18, v81 row_shr:1 row_mask:0xf bank_mask:0xf bound_ctrl:1
;     __device__ __forceinline__ f32x4 conv4s(const f32x4 c4, const f32x4 pv, int t, const f32x4 w0, const f32x4 w1, const f32x4 w2, const f32x4 bsv) const {
;         f32x4 p1, p2;
; #pragma unroll
;         for (int e = 0; e < 4; ++e) { p1[e] = dpp_f<0x111>(0.f, c4[e]); p2[e] = dpp_f<0x112>(0.f, c4[e]); const float q1 = dpp_f<0x101>(0.f, pv[e]);
;             p1[e] = t == 0 ? q1 : p1[e]; p2[e] = t < 2 ? pv[e] : p2[e]; }
;         f32x4 uu = bsv + w2 * c4 + w1 * p1 + w0 * p2;
;         asm volatile("" : "+v"(uu));
;         return uu;
;     __device__ __forceinline__ void sample(f32x4 (&acc)[2][2][4][2], const Unit& u, int row0t, int wr, int wc, int fr, int fq) const {
;     ...
;             if (step != 2) { const unsigned cso = (unsigned)((DFF + ca + 4 * n) * 4);
;                 w0 = *(const f32x4*)((const char*)cw + cso); w1 = *(const f32x4*)((const char*)(cw + DFF2) + cso); w2 = *(const f32x4*)((const char*)(cw + 2 * DFF2) + cso); bsv = *(const f32x4*)((const char*)cb + cso);
;                 wk[0] = w0; wk[1] = w1; wk[2] = w2; wk[3] = bsv; }
;             else { w0 = wk[0]; w1 = wk[1]; w2 = wk[2]; bsv = wk[3]; }
; #pragma unroll
;             for (int mp = 0; mp < 4; mp += 4) {
;             f32x4 pv[4];
; #pragma unroll
;             for (int k = 0; k < 4; ++k) { pv[k] = (f32x4){0.f, 0.f, 0.f, 0.f}; if (t < 2) pv[k] = *(const f32x4*)((const char*)st + stoff + (unsigned)(((16 * ai + 2 * (mp + k)) * 2 * DFF2 + DFF + 4 * n) * 4)); }
	v_mov_b32_dpp v133, v213 row_shl:1 row_mask:0xf bank_mask:0xf bound_ctrl:1
	v_pk_fma_f32 v[78:79], v[142:143], v[156:157], v[78:79]
	v_cndmask_b32_e64 v133, v18, v133, s[6:7]
	v_cndmask_b32_e64 v159, v164, v211, s[4:5]
	v_mov_b32_dpp v18, v82 row_shr:1 row_mask:0xf bank_mask:0xf bound_ctrl:1
	v_mov_b32_dpp v157, v82 row_shr:2 row_mask:0xf bank_mask:0xf bound_ctrl:1
	v_mov_b32_dpp v156, v214 row_shl:1 row_mask:0xf bank_mask:0xf bound_ctrl:1
	v_pk_fma_f32 v[78:79], v[138:139], v[158:159], v[78:79]
	v_cndmask_b32_e64 v156, v18, v156, s[6:7]
	v_cndmask_b32_e64 v158, v157, v214, s[4:5]
	v_mov_b32_dpp v135, v81 row_shr:2 row_mask:0xf bank_mask:0xf bound_ctrl:1
	v_mov_b32_dpp v18, v83 row_shr:1 row_mask:0xf bank_mask:0xf bound_ctrl:1
	v_mov_b32_dpp v157, v215 row_shl:1 row_mask:0xf bank_mask:0xf bound_ctrl:1
	v_pk_fma_f32 v[80:81], v[80:81], v[144:145], v[148:149]
	v_cndmask_b32_e64 v157, v18, v157, s[6:7]
	v_pk_fma_f32 v[80:81], v[140:141], v[132:133], v[80:81]
	v_cndmask_b32_e64 v135, v135, v213, s[4:5]
	v_mov_b32_dpp v18, v96 row_shr:1 row_mask:0xf bank_mask:0xf bound_ctrl:1
	v_mov_b32_dpp v133, v96 row_shr:2 row_mask:0xf bank_mask:0xf bound_ctrl:1
	v_mov_b32_dpp v132, v216 row_shl:1 row_mask:0xf bank_mask:0xf bound_ctrl:1
	v_pk_fma_f32 v[80:81], v[136:137], v[134:135], v[80:81]
	v_cndmask_b32_e64 v132, v18, v132, s[6:7]
	v_cndmask_b32_e64 v134, v133, v216, s[4:5]
	v_mov_b32_dpp v18, v97 row_shr:1 row_mask:0xf bank_mask:0xf bound_ctrl:1
	v_mov_b32_dpp v135, v97 row_shr:2 row_mask:0xf bank_mask:0xf bound_ctrl:1
	v_mov_b32_dpp v133, v217 row_shl:1 row_mask:0xf bank_mask:0xf bound_ctrl:1
	v_cndmask_b32_e64 v133, v18, v133, s[6:7]
	v_cndmask_b32_e64 v135, v135, v217, s[4:5]
	v_mov_b32_dpp v18, v98 row_shr:1 row_mask:0xf bank_mask:0xf bound_ctrl:1
	v_mov_b32_dpp v153, v98 row_shr:2 row_mask:0xf bank_mask:0xf bound_ctrl:1
	v_mov_b32_dpp v152, v218 row_shl:1 row_mask:0xf bank_mask:0xf bound_ctrl:1
	v_mov_b32_dpp v159, v83 row_shr:2 row_mask:0xf bank_mask:0xf bound_ctrl:1
	v_pk_fma_f32 v[82:83], v[82:83], v[146:147], v[150:151]
	v_cndmask_b32_e64 v152, v18, v152, s[6:7]
	v_cndmask_b32_e64 v154, v153, v218, s[4:5]
	v_pk_fma_f32 v[82:83], v[142:143], v[156:157], v[82:83]
	v_mov_b32_dpp v18, v99 row_shr:1 row_mask:0xf bank_mask:0xf bound_ctrl:1
	v_mov_b32_dpp v153, v219 row_shl:1 row_mask:0xf bank_mask:0xf bound_ctrl:1
	v_cndmask_b32_e64 v153, v18, v153, s[6:7]
	v_mov_b32_dpp v156, v99 row_shr:2 row_mask:0xf bank_mask:0xf bound_ctrl:1
	v_pk_fma_f32 v[98:99], v[98:99], v[146:147], v[150:151]
	v_pk_fma_f32 v[96:97], v[96:97], v[144:145], v[148:149]
	v_cndmask_b32_e64 v159, v159, v215, s[4:5]
	v_cndmask_b32_e64 v155, v156, v219, s[4:5]
	v_pk_fma_f32 v[98:99], v[142:143], v[152:153], v[98:99]
	v_pk_fma_f32 v[96:97], v[140:141], v[132:133], v[96:97]
	v_pk_fma_f32 v[82:83], v[138:139], v[158:159], v[82:83]
	v_pk_fma_f32 v[98:99], v[138:139], v[154:155], v[98:99]
	v_pk_fma_f32 v[96:97], v[136:137], v[134:135], v[96:97]
	s_nop 0
	v_add_u32_e32 v170, 0x2c00, v176
	global_load_dwordx4 v[136:139], v170, s[0:1]
	global_load_dwordx4 v[140:143], v170, s[8:9]
	global_load_dwordx4 v[132:135], v170, s[96:97]
	global_load_dwordx4 v[144:147], v170, s[66:67]
	v_mov_b32_e32 v152, 0
	v_mov_b32_e32 v156, 0
	v_mov_b32_e32 v157, 0
	v_mov_b32_e32 v158, 0
	v_mov_b32_e32 v159, 0
	v_mov_b32_e32 v153, 0
	v_mov_b32_e32 v154, 0
	v_mov_b32_e32 v155, 0
	v_mov_b32_e32 v148, 0
	v_mov_b32_e32 v166, 0
	v_mov_b32_e32 v167, 0
	v_mov_b32_e32 v168, 0
	v_mov_b32_e32 v169, 0
	v_mov_b32_e32 v149, 0
	v_mov_b32_e32 v150, 0
	v_mov_b32_e32 v151, 0
	s_nop 0
	s_nop 0
	v_mov_b32_e32 v160, v19
	v_mov_b32_dpp v18, v92 row_shr:1 row_mask:0xf bank_mask:0xf bound_ctrl:1
	v_mov_b32_dpp v161, v92 row_shr:2 row_mask:0xf bank_mask:0xf bound_ctrl:1
	v_mov_b32_e32 v204, 0
	v_mov_b32_e32 v205, 0
	v_mov_b32_e32 v206, 0
	v_mov_b32_e32 v207, 0
	v_mov_b32_e32 v208, 0
	v_mov_b32_e32 v209, 0
	v_mov_b32_e32 v210, 0
	v_mov_b32_e32 v211, 0
	v_mov_b32_e32 v212, 0
	v_mov_b32_e32 v213, 0
	v_mov_b32_e32 v214, 0
	v_mov_b32_e32 v215, 0
	v_mov_b32_e32 v216, 0
	v_mov_b32_e32 v217, 0
	v_mov_b32_e32 v218, 0
	v_mov_b32_e32 v219, 0
	s_waitcnt vmcnt(0)
	s_and_saveexec_b64 s[100:101], s[4:5]
	s_cbranch_execz .Lspp_5
	s_mov_b64 s[98:99], 0x2c10
	v_lshl_add_u64 v[194:195], v[172:173], 0, s[98:99]
	global_load_dwordx4 v[204:207], v[194:195], off
	s_mov_b64 s[98:99], 0x18c10
	v_lshl_add_u64 v[194:195], v[172:173], 0, s[98:99]
	global_load_dwordx4 v[208:211], v[194:195], off
	s_mov_b64 s[98:99], 0x2ec10
	v_lshl_add_u64 v[194:195], v[172:173], 0, s[98:99]
	global_load_dwordx4 v[212:215], v[194:195], off
	s_mov_b64 s[98:99], 0x44c10
	v_lshl_add_u64 v[194:195], v[172:173], 0, s[98:99]
	global_load_dwordx4 v[216:219], v[194:195], off
; __device__ __forceinline__ unsigned cvt_pk_bf16(float lo, float hi) { const bf16x2_t r = __builtin_convertvector((f32x2){lo, hi}, bf16x2_t); return __builtin_bit_cast(unsigned, r); }
; __device__ __forceinline__ float silu_f(float x) { return x * __builtin_amdgcn_rcpf(1.0f + __expf(-x)); }
;     __device__ __forceinline__ f32x4 conv4s(const f32x4 c4, const f32x4 pv, int t, const f32x4 w0, const f32x4 w1, const f32x4 w2, const f32x4 bsv) const {
;         f32x4 p1, p2;
; #pragma unroll
;         for (int e = 0; e < 4; ++e) { p1[e] = dpp_f<0x111>(0.f, c4[e]); p2[e] = dpp_f<0x112>(0.f, c4[e]); const float q1 = dpp_f<0x101>(0.f, pv[e]);
;             p1[e] = t == 0 ? q1 : p1[e]; p2[e] = t < 2 ? pv[e] : p2[e]; }
;         f32x4 uu = bsv + w2 * c4 + w1 * p1 + w0 * p2;
;         asm volatile("" : "+v"(uu));
;         return uu;
;     }
;     __device__ __forceinline__ void sample(f32x4 (&acc)[2][2][4][2], const Unit& u, int row0t, int wr, int wc, int fr, int fq) const {
;     ...
; #pragma unroll
;             for (int mp = 0; mp < 4; mp += 4) {
;             f32x4 pv[4];
; #pragma unroll
;             for (int k = 0; k < 4; ++k) { pv[k] = (f32x4){0.f, 0.f, 0.f, 0.f}; if (t < 2) pv[k] = *(const f32x4*)((const char*)st + stoff + (unsigned)(((16 * ai + 2 * (mp + k)) * 2 * DFF2 + DFF + 4 * n) * 4)); }
; #pragma unroll
;             for (int k = 0; k < 4; ++k) { const int m = mp + k;
;                 const f32x4 uu = conv4s(acc[ai][1][m][n], pv[k], t, w0, w1, w2, bsv);
;                 const f32x4 ua = acc[ai][0][m][n];
;                 u32x2 w; w.x = cvt_pk_bf16(silu_f(ua[0]) * uu[0], silu_f(ua[1]) * uu[1]); w.y = cvt_pk_bf16(silu_f(ua[2]) * uu[2], silu_f(ua[3]) * uu[3]);
;                 if ((step & 1) == 0) pend[m] = w;
;                 else { u32x4 o; if (n == 1) { o.x = pend[m].x; o.y = pend[m].y; o.z = w.x; o.w = w.y; } else { o.x = w.x; o.y = w.y; o.z = pend[m].x; o.w = pend[m].y; }
;                     *(u32x4*)((char*)act + rowoff0 + (unsigned)((ai * HALF + m * 16) * DFF * 2) + (unsigned)(ca * 2)) = o; }
.Lspp_5:
	s_or_b64 exec, exec, s[100:101]
	s_nop 4
	v_mov_b32_dpp v160, v178 row_shl:1 row_mask:0xf bank_mask:0xf
	v_cndmask_b32_e64 v160, v18, v160, s[6:7]
	v_cndmask_b32_e64 v156, v161, v178, s[4:5]
	s_nop 0
	s_nop 0
	v_mov_b32_dpp v18, v93 row_shr:1 row_mask:0xf bank_mask:0xf bound_ctrl:1
	v_mov_b32_dpp v162, v93 row_shr:2 row_mask:0xf bank_mask:0xf bound_ctrl:1
	v_mov_b32_dpp v161, v179 row_shl:1 row_mask:0xf bank_mask:0xf bound_ctrl:1
	v_cndmask_b32_e64 v161, v18, v161, s[6:7]
	v_cndmask_b32_e64 v157, v162, v179, s[4:5]
	v_mov_b32_dpp v18, v94 row_shr:1 row_mask:0xf bank_mask:0xf bound_ctrl:1
	v_mov_b32_dpp v163, v94 row_shr:2 row_mask:0xf bank_mask:0xf bound_ctrl:1
	v_mov_b32_dpp v162, v180 row_shl:1 row_mask:0xf bank_mask:0xf bound_ctrl:1
	v_cndmask_b32_e64 v162, v18, v162, s[6:7]
	v_cndmask_b32_e64 v158, v163, v180, s[4:5]
	v_mov_b32_dpp v18, v95 row_shr:1 row_mask:0xf bank_mask:0xf bound_ctrl:1
	v_mov_b32_dpp v163, v181 row_shl:1 row_mask:0xf bank_mask:0xf bound_ctrl:1
	v_mov_b32_dpp v164, v95 row_shr:2 row_mask:0xf bank_mask:0xf bound_ctrl:1
	v_cndmask_b32_e64 v163, v18, v163, s[6:7]
	v_pk_fma_f32 v[94:95], v[94:95], v[142:143], v[146:147]
	v_pk_fma_f32 v[92:93], v[92:93], v[140:141], v[144:145]
	v_cndmask_b32_e64 v159, v164, v181, s[4:5]
	v_pk_fma_f32 v[94:95], v[138:139], v[162:163], v[94:95]
	v_pk_fma_f32 v[92:93], v[136:137], v[160:161], v[92:93]
	v_pk_fma_f32 v[164:165], v[134:135], v[158:159], v[94:95]
	v_pk_fma_f32 v[162:163], v[132:133], v[156:157], v[92:93]
	s_nop 0
	v_mov_b32_dpp v18, v88 row_shr:1 row_mask:0xf bank_mask:0xf bound_ctrl:1
	v_mov_b32_dpp v93, v88 row_shr:2 row_mask:0xf bank_mask:0xf bound_ctrl:1
	v_mov_b32_dpp v92, v182 row_shl:1 row_mask:0xf bank_mask:0xf bound_ctrl:1
	v_cndmask_b32_e64 v92, v18, v92, s[6:7]
	v_cndmask_b32_e64 v94, v93, v182, s[4:5]
	v_mov_b32_dpp v18, v89 row_shr:1 row_mask:0xf bank_mask:0xf bound_ctrl:1
	v_mov_b32_dpp v95, v89 row_shr:2 row_mask:0xf bank_mask:0xf bound_ctrl:1
	v_mov_b32_dpp v93, v183 row_shl:1 row_mask:0xf bank_mask:0xf bound_ctrl:1
	v_cndmask_b32_e64 v93, v18, v93, s[6:7]
	v_cndmask_b32_e64 v95, v95, v183, s[4:5]
	v_mov_b32_dpp v18, v90 row_shr:1 row_mask:0xf bank_mask:0xf bound_ctrl:1
	v_mov_b32_dpp v153, v90 row_shr:2 row_mask:0xf bank_mask:0xf bound_ctrl:1
	v_mov_b32_dpp v152, v184 row_shl:1 row_mask:0xf bank_mask:0xf bound_ctrl:1
	v_cndmask_b32_e64 v152, v18, v152, s[6:7]
	v_cndmask_b32_e64 v154, v153, v184, s[4:5]
	v_mov_b32_dpp v18, v91 row_shr:1 row_mask:0xf bank_mask:0xf bound_ctrl:1
	v_mov_b32_dpp v153, v185 row_shl:1 row_mask:0xf bank_mask:0xf bound_ctrl:1
	v_mov_b32_dpp v156, v91 row_shr:2 row_mask:0xf bank_mask:0xf bound_ctrl:1
	v_cndmask_b32_e64 v153, v18, v153, s[6:7]
	v_pk_fma_f32 v[90:91], v[90:91], v[142:143], v[146:147]
	v_pk_fma_f32 v[88:89], v[88:89], v[140:141], v[144:145]
	v_cndmask_b32_e64 v155, v156, v185, s[4:5]
	v_pk_fma_f32 v[90:91], v[138:139], v[152:153], v[90:91]
	v_pk_fma_f32 v[88:89], v[136:137], v[92:93], v[88:89]
	v_pk_fma_f32 v[160:161], v[134:135], v[154:155], v[90:91]
	v_pk_fma_f32 v[158:159], v[132:133], v[94:95], v[88:89]
	s_nop 0
	v_mov_b32_dpp v18, v84 row_shr:1 row_mask:0xf bank_mask:0xf bound_ctrl:1
	v_mov_b32_dpp v89, v84 row_shr:2 row_mask:0xf bank_mask:0xf bound_ctrl:1
	v_mov_b32_dpp v88, v186 row_shl:1 row_mask:0xf bank_mask:0xf bound_ctrl:1
	v_cndmask_b32_e64 v88, v18, v88, s[6:7]
	v_cndmask_b32_e64 v90, v89, v186, s[4:5]
	v_mov_b32_dpp v18, v85 row_shr:1 row_mask:0xf bank_mask:0xf bound_ctrl:1
	v_mov_b32_dpp v89, v187 row_shl:1 row_mask:0xf bank_mask:0xf bound_ctrl:1
	v_cndmask_b32_e64 v89, v18, v89, s[6:7]
	v_mov_b32_dpp v93, v86 row_shr:2 row_mask:0xf bank_mask:0xf bound_ctrl:1
	v_mov_b32_dpp v18, v86 row_shr:1 row_mask:0xf bank_mask:0xf bound_ctrl:1
	v_mov_b32_dpp v92, v188 row_shl:1 row_mask:0xf bank_mask:0xf bound_ctrl:1
	v_cndmask_b32_e64 v92, v18, v92, s[6:7]
	v_cndmask_b32_e64 v94, v93, v188, s[4:5]
	v_mov_b32_dpp v18, v87 row_shr:1 row_mask:0xf bank_mask:0xf bound_ctrl:1
	v_mov_b32_dpp v93, v189 row_shl:1 row_mask:0xf bank_mask:0xf bound_ctrl:1
	v_mov_b32_dpp v91, v85 row_shr:2 row_mask:0xf bank_mask:0xf bound_ctrl:1
	v_mov_b32_dpp v95, v87 row_shr:2 row_mask:0xf bank_mask:0xf bound_ctrl:1
	v_cndmask_b32_e64 v93, v18, v93, s[6:7]
	v_pk_fma_f32 v[86:87], v[86:87], v[142:143], v[146:147]
	v_pk_fma_f32 v[84:85], v[84:85], v[140:141], v[144:145]
	v_cndmask_b32_e64 v91, v91, v187, s[4:5]
	v_cndmask_b32_e64 v95, v95, v189, s[4:5]
	v_pk_fma_f32 v[86:87], v[138:139], v[92:93], v[86:87]
	v_pk_fma_f32 v[84:85], v[136:137], v[88:89], v[84:85]
	v_pk_fma_f32 v[156:157], v[134:135], v[94:95], v[86:87]
	v_pk_fma_f32 v[154:155], v[132:133], v[90:91], v[84:85]
	s_nop 0
	v_mov_b32_dpp v18, v68 row_shr:1 row_mask:0xf bank_mask:0xf bound_ctrl:1
	v_mov_b32_dpp v85, v68 row_shr:2 row_mask:0xf bank_mask:0xf bound_ctrl:1
	v_mov_b32_dpp v84, v190 row_shl:1 row_mask:0xf bank_mask:0xf bound_ctrl:1
	v_cndmask_b32_e64 v84, v18, v84, s[6:7]
	v_cndmask_b32_e64 v86, v85, v190, s[4:5]
	v_mov_b32_dpp v18, v69 row_shr:1 row_mask:0xf bank_mask:0xf bound_ctrl:1
	v_mov_b32_dpp v85, v191 row_shl:1 row_mask:0xf bank_mask:0xf bound_ctrl:1
	v_cndmask_b32_e64 v85, v18, v85, s[6:7]
	v_mov_b32_dpp v89, v70 row_shr:2 row_mask:0xf bank_mask:0xf bound_ctrl:1
	v_mov_b32_dpp v18, v70 row_shr:1 row_mask:0xf bank_mask:0xf bound_ctrl:1
	v_mov_b32_dpp v88, v192 row_shl:1 row_mask:0xf bank_mask:0xf bound_ctrl:1
	v_cndmask_b32_e64 v88, v18, v88, s[6:7]
	v_cndmask_b32_e64 v90, v89, v192, s[4:5]
	v_mov_b32_dpp v18, v71 row_shr:1 row_mask:0xf bank_mask:0xf bound_ctrl:1
	v_mov_b32_dpp v89, v193 row_shl:1 row_mask:0xf bank_mask:0xf bound_ctrl:1
; __device__ __forceinline__ unsigned cvt_pk_bf16(float lo, float hi) { const bf16x2_t r = __builtin_convertvector((f32x2){lo, hi}, bf16x2_t); return __builtin_bit_cast(unsigned, r); }
; __device__ __forceinline__ float silu_f(float x) { return x * __builtin_amdgcn_rcpf(1.0f + __expf(-x)); }
;     __device__ __forceinline__ void sample(f32x4 (&acc)[2][2][4][2], const Unit& u, int row0t, int wr, int wc, int fr, int fq) const {
;     ...
;         for (int step = 0; step < 4; ++step) {
;             const int n = (step == 1 || step == 2) ? 1 : 0, ai = step >> 1;
;             f32x4 w0, w1, w2, bsv;
;             if (step != 2) { const unsigned cso = (unsigned)((DFF + ca + 4 * n) * 4);
;                 w0 = *(const f32x4*)((const char*)cw + cso); w1 = *(const f32x4*)((const char*)(cw + DFF2) + cso); w2 = *(const f32x4*)((const char*)(cw + 2 * DFF2) + cso); bsv = *(const f32x4*)((const char*)cb + cso);
;                 wk[0] = w0; wk[1] = w1; wk[2] = w2; wk[3] = bsv; }
;             else { w0 = wk[0]; w1 = wk[1]; w2 = wk[2]; bsv = wk[3]; }
; #pragma unroll
;             for (int mp = 0; mp < 4; mp += 4) {
;             f32x4 pv[4];
; #pragma unroll
;             for (int k = 0; k < 4; ++k) { pv[k] = (f32x4){0.f, 0.f, 0.f, 0.f}; if (t < 2) pv[k] = *(const f32x4*)((const char*)st + stoff + (unsigned)(((16 * ai + 2 * (mp + k)) * 2 * DFF2 + DFF + 4 * n) * 4)); }
; #pragma unroll
;             for (int k = 0; k < 4; ++k) { const int m = mp + k;
;                 const f32x4 uu = conv4s(acc[ai][1][m][n], pv[k], t, w0, w1, w2, bsv);
;                 const f32x4 ua = acc[ai][0][m][n];
;                 u32x2 w; w.x = cvt_pk_bf16(silu_f(ua[0]) * uu[0], silu_f(ua[1]) * uu[1]); w.y = cvt_pk_bf16(silu_f(ua[2]) * uu[2], silu_f(ua[3]) * uu[3]);
;                 if ((step & 1) == 0) pend[m] = w;
;                 else { u32x4 o; if (n == 1) { o.x = pend[m].x; o.y = pend[m].y; o.z = w.x; o.w = w.y; } else { o.x = w.x; o.y = w.y; o.z = pend[m].x; o.w = pend[m].y; }
;                     *(u32x4*)((char*)act + rowoff0 + (unsigned)((ai * HALF + m * 16) * DFF * 2) + (unsigned)(ca * 2)) = o; }
;                 __builtin_amdgcn_sched_barrier(0);
;             }
	v_mov_b32_dpp v87, v69 row_shr:2 row_mask:0xf bank_mask:0xf bound_ctrl:1
	v_mov_b32_dpp v91, v71 row_shr:2 row_mask:0xf bank_mask:0xf bound_ctrl:1
	v_cndmask_b32_e64 v89, v18, v89, s[6:7]
	v_pk_fma_f32 v[70:71], v[70:71], v[142:143], v[146:147]
	v_pk_fma_f32 v[68:69], v[68:69], v[140:141], v[144:145]
	v_cndmask_b32_e64 v87, v87, v191, s[4:5]
	v_cndmask_b32_e64 v91, v91, v193, s[4:5]
	v_pk_fma_f32 v[70:71], v[138:139], v[88:89], v[70:71]
	v_pk_fma_f32 v[68:69], v[136:137], v[84:85], v[68:69]
	v_pk_fma_f32 v[152:153], v[134:135], v[90:91], v[70:71]
	v_pk_fma_f32 v[150:151], v[132:133], v[86:87], v[68:69]
	s_nop 0
	v_add_u32_e32 v18, 0x2c10, v176
	global_load_dwordx4 v[84:87], v18, s[0:1]
	global_load_dwordx4 v[88:91], v18, s[8:9]
	global_load_dwordx4 v[68:71], v18, s[96:97]
	global_load_dwordx4 v[92:95], v18, s[66:67]
	v_mov_b32_e32 v140, 0
	v_mov_b32_e32 v144, 0
	v_mov_b32_e32 v145, 0
	v_mov_b32_e32 v146, 0
	v_mov_b32_e32 v147, 0
	v_mov_b32_e32 v141, 0
	v_mov_b32_e32 v142, 0
	v_mov_b32_e32 v143, 0
	v_mov_b32_e32 v132, 0
	v_mov_b32_e32 v136, 0
	v_mov_b32_e32 v137, 0
	v_mov_b32_e32 v138, 0
	v_mov_b32_e32 v139, 0
	v_mov_b32_e32 v133, 0
	v_mov_b32_e32 v134, 0
	v_mov_b32_e32 v135, 0
	v_mul_f32_e32 v18, 0xbfb8aa3b, v114
	v_exp_f32_e32 v18, v18
	s_movk_i32 s2, 0x1600
	v_add_f32_e32 v18, 1.0, v18
	v_rcp_f32_e32 v148, v18
	v_mul_f32_e32 v18, 0xbfb8aa3b, v115
	v_exp_f32_e32 v18, v18
	s_nop 0
	v_add_f32_e32 v18, 1.0, v18
	v_rcp_f32_e32 v149, v18
	v_mul_f32_e32 v18, 0xbfb8aa3b, v112
	v_exp_f32_e32 v18, v18
	v_pk_mul_f32 v[114:115], v[114:115], v[148:149]
	s_nop 0
	v_pk_mul_f32 v[114:115], v[114:115], v[164:165]
	v_add_f32_e32 v18, 1.0, v18
	v_cvt_pk_bf16_f32 v149, v114, v115
	v_rcp_f32_e32 v114, v18
	v_mul_f32_e32 v18, 0xbfb8aa3b, v113
	v_exp_f32_e32 v18, v18
	s_nop 0
	v_add_f32_e32 v18, 1.0, v18
	v_rcp_f32_e32 v115, v18
	v_mul_f32_e32 v18, 0xbfb8aa3b, v110
	v_exp_f32_e32 v18, v18
	v_pk_mul_f32 v[112:113], v[112:113], v[114:115]
	s_nop 0
	v_pk_mul_f32 v[112:113], v[112:113], v[162:163]
	v_add_f32_e32 v18, 1.0, v18
	v_cvt_pk_bf16_f32 v148, v112, v113
	v_rcp_f32_e32 v112, v18
	v_mul_f32_e32 v18, 0xbfb8aa3b, v111
	v_exp_f32_e32 v18, v18
	v_mov_b32_e32 v114, v19
	v_mov_b32_e32 v115, v19
	v_add_f32_e32 v18, 1.0, v18
	v_rcp_f32_e32 v113, v18
	v_mul_f32_e32 v18, 0xbfb8aa3b, v108
	v_exp_f32_e32 v18, v18
	v_mov_b32_e32 v178, 0
	v_mov_b32_e32 v179, 0
	v_mov_b32_e32 v180, 0
	v_mov_b32_e32 v181, 0
	v_mov_b32_e32 v182, 0
	v_mov_b32_e32 v183, 0
	v_mov_b32_e32 v184, 0
	v_mov_b32_e32 v185, 0
	v_mov_b32_e32 v186, 0
	v_mov_b32_e32 v187, 0
	v_mov_b32_e32 v188, 0
	v_mov_b32_e32 v189, 0
	v_mov_b32_e32 v190, 0
	v_mov_b32_e32 v191, 0
	v_mov_b32_e32 v192, 0
	v_mov_b32_e32 v193, 0
	s_waitcnt vmcnt(0)
	s_and_saveexec_b64 s[100:101], s[4:5]
	s_cbranch_execz .Lspp_6
	s_mov_b64 s[98:99], 0xb2c10
	v_lshl_add_u64 v[194:195], v[172:173], 0, s[98:99]
	global_load_dwordx4 v[178:181], v[194:195], off
	s_mov_b64 s[98:99], 0xc8c10
	v_lshl_add_u64 v[194:195], v[172:173], 0, s[98:99]
	global_load_dwordx4 v[182:185], v[194:195], off
	s_mov_b64 s[98:99], 0xdec10
	v_lshl_add_u64 v[194:195], v[172:173], 0, s[98:99]
	global_load_dwordx4 v[186:189], v[194:195], off
	s_mov_b64 s[98:99], 0xf4c10
	v_lshl_add_u64 v[194:195], v[172:173], 0, s[98:99]
	global_load_dwordx4 v[190:193], v[194:195], off
.Lspp_6:
	s_or_b64 exec, exec, s[100:101]
	s_nop 4
	v_mov_b32_dpp v114, v206 row_shl:1 row_mask:0xf bank_mask:0xf
	v_pk_mul_f32 v[110:111], v[110:111], v[112:113]
	v_mov_b32_dpp v115, v67 row_shr:2 row_mask:0xf bank_mask:0xf
	v_add_f32_e32 v18, 1.0, v18
	v_rcp_f32_e32 v112, v18
	v_mul_f32_e32 v18, 0xbfb8aa3b, v109
	v_exp_f32_e32 v18, v18
	v_pk_mul_f32 v[110:111], v[110:111], v[160:161]
	v_cndmask_b32_e64 v115, v115, v207, s[4:5]
	v_cvt_pk_bf16_f32 v111, v110, v111
	v_add_f32_e32 v18, 1.0, v18
	v_rcp_f32_e32 v113, v18
	v_mul_f32_e32 v18, 0xbfb8aa3b, v106
	v_exp_f32_e32 v18, v18
	v_pk_mul_f32 v[108:109], v[108:109], v[112:113]
	s_nop 0
	v_pk_mul_f32 v[108:109], v[108:109], v[158:159]
	v_add_f32_e32 v18, 1.0, v18
	v_cvt_pk_bf16_f32 v110, v108, v109
	v_rcp_f32_e32 v108, v18
	v_mul_f32_e32 v18, 0xbfb8aa3b, v107
	v_exp_f32_e32 v18, v18
	s_nop 0
	s_nop 0
	v_add_f32_e32 v18, 1.0, v18
	v_rcp_f32_e32 v109, v18
	v_mul_f32_e32 v18, 0xbfb8aa3b, v104
	v_exp_f32_e32 v18, v18
	v_mov_b32_dpp v112, v205 row_shl:1 row_mask:0xf bank_mask:0xf bound_ctrl:1
	v_pk_mul_f32 v[106:107], v[106:107], v[108:109]
	v_mov_b32_dpp v113, v66 row_shr:2 row_mask:0xf bank_mask:0xf bound_ctrl:1
	v_add_f32_e32 v18, 1.0, v18
	v_rcp_f32_e32 v108, v18
	v_mul_f32_e32 v18, 0xbfb8aa3b, v105
	v_exp_f32_e32 v18, v18
	v_pk_mul_f32 v[106:107], v[106:107], v[156:157]
	v_add_f32_e32 v18, 1.0, v18
	v_rcp_f32_e32 v109, v18
	v_mul_f32_e32 v18, 0xbfb8aa3b, v102
	v_exp_f32_e32 v18, v18
	v_cvt_pk_bf16_f32 v107, v106, v107
	v_pk_mul_f32 v[104:105], v[104:105], v[108:109]
	s_nop 0
	v_pk_mul_f32 v[104:105], v[104:105], v[154:155]
	v_add_f32_e32 v18, 1.0, v18
	v_cvt_pk_bf16_f32 v106, v104, v105
	v_rcp_f32_e32 v104, v18
	v_mul_f32_e32 v18, 0xbfb8aa3b, v103
	v_exp_f32_e32 v18, v18
	v_mov_b32_dpp v108, v204 row_shl:1 row_mask:0xf bank_mask:0xf bound_ctrl:1
	s_nop 0
	v_add_f32_e32 v18, 1.0, v18
	v_rcp_f32_e32 v105, v18
	v_mul_f32_e32 v18, 0xbfb8aa3b, v100
	v_exp_f32_e32 v18, v18
	v_mov_b32_dpp v109, v65 row_shr:2 row_mask:0xf bank_mask:0xf bound_ctrl:1
	v_pk_mul_f32 v[102:103], v[102:103], v[104:105]
	v_cndmask_b32_e64 v109, v109, v205, s[4:5]
	v_add_f32_e32 v18, 1.0, v18
	v_rcp_f32_e32 v104, v18
	v_mul_f32_e32 v18, 0xbfb8aa3b, v101
	v_exp_f32_e32 v18, v18
	v_pk_mul_f32 v[102:103], v[102:103], v[152:153]
	v_add_f32_e32 v18, 1.0, v18
	v_rcp_f32_e32 v105, v18
; __device__ __forceinline__ unsigned cvt_pk_bf16(float lo, float hi) { const bf16x2_t r = __builtin_convertvector((f32x2){lo, hi}, bf16x2_t); return __builtin_bit_cast(unsigned, r); }
; __device__ __forceinline__ float silu_f(float x) { return x * __builtin_amdgcn_rcpf(1.0f + __expf(-x)); }
;     __device__ __forceinline__ void sample(f32x4 (&acc)[2][2][4][2], const Unit& u, int row0t, int wr, int wc, int fr, int fq) const {
;     ...
; #pragma unroll
;             for (int mp = 0; mp < 4; mp += 4) {
;             f32x4 pv[4];
; #pragma unroll
;             for (int k = 0; k < 4; ++k) { pv[k] = (f32x4){0.f, 0.f, 0.f, 0.f}; if (t < 2) pv[k] = *(const f32x4*)((const char*)st + stoff + (unsigned)(((16 * ai + 2 * (mp + k)) * 2 * DFF2 + DFF + 4 * n) * 4)); }
; #pragma unroll
;             for (int k = 0; k < 4; ++k) { const int m = mp + k;
;                 const f32x4 uu = conv4s(acc[ai][1][m][n], pv[k], t, w0, w1, w2, bsv);
;                 const f32x4 ua = acc[ai][0][m][n];
;                 u32x2 w; w.x = cvt_pk_bf16(silu_f(ua[0]) * uu[0], silu_f(ua[1]) * uu[1]); w.y = cvt_pk_bf16(silu_f(ua[2]) * uu[2], silu_f(ua[3]) * uu[3]);
;                 if ((step & 1) == 0) pend[m] = w;
;                 else { u32x4 o; if (n == 1) { o.x = pend[m].x; o.y = pend[m].y; o.z = w.x; o.w = w.y; } else { o.x = w.x; o.y = w.y; o.z = pend[m].x; o.w = pend[m].y; }
;                     *(u32x4*)((char*)act + rowoff0 + (unsigned)((ai * HALF + m * 16) * DFF * 2) + (unsigned)(ca * 2)) = o; }
;                 __builtin_amdgcn_sched_barrier(0);
;             }
	v_mul_lo_u32 v18, v174, s2
	v_cvt_pk_bf16_f32 v103, v102, v103
	v_pk_mul_f32 v[100:101], v[100:101], v[104:105]
	s_nop 0
	s_nop 0
	v_pk_mul_f32 v[100:101], v[100:101], v[150:151]
	v_mov_b32_dpp v104, v64 row_shr:1 row_mask:0xf bank_mask:0xf bound_ctrl:1
	v_mov_b32_dpp v105, v64 row_shr:2 row_mask:0xf bank_mask:0xf bound_ctrl:1
	v_cndmask_b32_e64 v104, v104, v108, s[6:7]
	v_cndmask_b32_e64 v108, v105, v204, s[4:5]
	v_cvt_pk_bf16_f32 v102, v100, v101
	v_mov_b32_dpp v105, v65 row_shr:1 row_mask:0xf bank_mask:0xf bound_ctrl:1
	v_cndmask_b32_e64 v105, v105, v112, s[6:7]
	v_pk_fma_f32 v[64:65], v[64:65], v[88:89], v[92:93]
	s_nop 0
	v_pk_fma_f32 v[64:65], v[84:85], v[104:105], v[64:65]
	v_mul_f32_e32 v104, 0xbfb8aa3b, v128
	v_mul_f32_e32 v105, 0xbfb8aa3b, v129
	v_exp_f32_e32 v104, v104
	v_exp_f32_e32 v105, v105
	v_mov_b32_dpp v112, v66 row_shr:1 row_mask:0xf bank_mask:0xf bound_ctrl:1
	v_cndmask_b32_e64 v112, v112, v114, s[6:7]
	v_cndmask_b32_e64 v114, v113, v206, s[4:5]
	s_nop 0
	v_add_f32_e32 v104, 1.0, v104
	v_add_f32_e32 v105, 1.0, v105
	v_mov_b32_dpp v113, v67 row_shr:1 row_mask:0xf bank_mask:0xf bound_ctrl:1
	v_mov_b32_dpp v144, v207 row_shl:1 row_mask:0xf bank_mask:0xf bound_ctrl:1
	v_rcp_f32_e32 v104, v104
	v_rcp_f32_e32 v105, v105
	v_cndmask_b32_e64 v113, v113, v144, s[6:7]
	v_pk_fma_f32 v[66:67], v[66:67], v[90:91], v[94:95]
	v_pk_fma_f32 v[64:65], v[68:69], v[108:109], v[64:65]
	v_pk_fma_f32 v[66:67], v[86:87], v[112:113], v[66:67]
	v_pk_mul_f32 v[104:105], v[128:129], v[104:105]
	v_pk_fma_f32 v[66:67], v[70:71], v[114:115], v[66:67]
	v_lshlrev_b32_e32 v100, 1, v175
	v_mov_b32_e32 v101, v19
	v_pk_mul_f32 v[64:65], v[104:105], v[64:65]
	s_nop 0
	v_cvt_pk_bf16_f32 v150, v64, v65
	v_mul_f32_e32 v64, 0xbfb8aa3b, v130
	v_mul_f32_e32 v65, 0xbfb8aa3b, v131
	v_exp_f32_e32 v64, v64
	v_exp_f32_e32 v65, v65
	v_add_f32_e32 v64, 1.0, v64
	v_add_f32_e32 v65, 1.0, v65
	v_rcp_f32_e32 v64, v64
	v_rcp_f32_e32 v65, v65
	s_nop 0
	v_pk_mul_f32 v[64:65], v[130:131], v[64:65]
	s_nop 0
	v_pk_mul_f32 v[64:65], v[64:65], v[66:67]
	s_nop 0
	v_cvt_pk_bf16_f32 v151, v64, v65
	v_lshl_add_u64 v[64:65], s[70:71], 0, v[18:19]
	v_lshl_add_u64 v[114:115], v[64:65], 0, v[100:101]
	global_store_dwordx4 v[114:115], v[148:151], off
	s_nop 0
	s_nop 0
	s_nop 0
	v_mov_b32_dpp v18, v60 row_shr:1 row_mask:0xf bank_mask:0xf bound_ctrl:1
	v_mov_b32_dpp v65, v60 row_shr:2 row_mask:0xf bank_mask:0xf bound_ctrl:1
	v_mov_b32_dpp v64, v208 row_shl:1 row_mask:0xf bank_mask:0xf bound_ctrl:1
	v_cndmask_b32_e64 v64, v18, v64, s[6:7]
	v_cndmask_b32_e64 v66, v65, v208, s[4:5]
	v_mov_b32_dpp v18, v61 row_shr:1 row_mask:0xf bank_mask:0xf bound_ctrl:1
	v_mov_b32_dpp v65, v209 row_shl:1 row_mask:0xf bank_mask:0xf bound_ctrl:1
	v_cndmask_b32_e64 v65, v18, v65, s[6:7]
	v_mov_b32_dpp v101, v62 row_shr:2 row_mask:0xf bank_mask:0xf
	v_mov_b32_dpp v100, v210 row_shl:1 row_mask:0xf bank_mask:0xf bound_ctrl:1
	v_mov_b32_dpp v18, v62 row_shr:1 row_mask:0xf bank_mask:0xf bound_ctrl:1
	v_cndmask_b32_e64 v100, v18, v100, s[6:7]
	v_cndmask_b32_e64 v104, v101, v210, s[4:5]
	v_mov_b32_dpp v18, v63 row_shr:1 row_mask:0xf bank_mask:0xf bound_ctrl:1
	v_mov_b32_dpp v101, v211 row_shl:1 row_mask:0xf bank_mask:0xf bound_ctrl:1
	v_mov_b32_dpp v67, v61 row_shr:2 row_mask:0xf bank_mask:0xf bound_ctrl:1
	v_cndmask_b32_e64 v101, v18, v101, s[6:7]
	v_pk_fma_f32 v[60:61], v[60:61], v[88:89], v[92:93]
	v_mul_f32_e32 v18, 0xbfb8aa3b, v124
	v_pk_fma_f32 v[60:61], v[84:85], v[64:65], v[60:61]
	v_exp_f32_e32 v18, v18
	v_mul_f32_e32 v64, 0xbfb8aa3b, v125
	v_exp_f32_e32 v65, v64
	v_cndmask_b32_e64 v67, v67, v209, s[4:5]
	v_add_f32_e32 v18, 1.0, v18
	v_rcp_f32_e32 v64, v18
	v_add_f32_e32 v18, 1.0, v65
	v_mul_f32_e32 v65, 0xbfb8aa3b, v126
	v_pk_fma_f32 v[60:61], v[68:69], v[66:67], v[60:61]
	v_exp_f32_e32 v66, v65
	v_mul_f32_e32 v65, 0xbfb8aa3b, v127
	v_exp_f32_e32 v67, v65
	s_nop 0
	v_rcp_f32_e32 v65, v18
	v_add_f32_e32 v18, 1.0, v66
	v_mov_b32_dpp v105, v63 row_shr:2 row_mask:0xf bank_mask:0xf bound_ctrl:1
	v_pk_fma_f32 v[62:63], v[62:63], v[90:91], v[94:95]
	v_rcp_f32_e32 v66, v18
	v_add_f32_e32 v18, 1.0, v67
	v_cndmask_b32_e64 v105, v105, v211, s[4:5]
	v_pk_fma_f32 v[62:63], v[86:87], v[100:101], v[62:63]
	v_rcp_f32_e32 v67, v18
	v_pk_fma_f32 v[62:63], v[70:71], v[104:105], v[62:63]
	v_pk_mul_f32 v[64:65], v[124:125], v[64:65]
	s_mov_b32 s2, 0x16000
	v_pk_mul_f32 v[60:61], v[64:65], v[60:61]
	s_nop 0
	v_cvt_pk_bf16_f32 v112, v60, v61
	v_pk_mul_f32 v[60:61], v[126:127], v[66:67]
	s_nop 0
	v_pk_mul_f32 v[60:61], v[60:61], v[62:63]
	s_nop 0
	v_cvt_pk_bf16_f32 v113, v60, v61
	v_add_co_u32_e32 v60, vcc, s2, v114
	s_nop 1
	v_addc_co_u32_e32 v61, vcc, 0, v115, vcc
	global_store_dwordx4 v[60:61], v[110:113], off
	s_nop 0
	s_nop 0
	s_nop 0
	v_mov_b32_dpp v18, v56 row_shr:1 row_mask:0xf bank_mask:0xf bound_ctrl:1
	v_mov_b32_dpp v61, v56 row_shr:2 row_mask:0xf bank_mask:0xf bound_ctrl:1
	v_mov_b32_dpp v60, v212 row_shl:1 row_mask:0xf bank_mask:0xf bound_ctrl:1
	v_cndmask_b32_e64 v60, v18, v60, s[6:7]
	v_cndmask_b32_e64 v62, v61, v212, s[4:5]
	v_mov_b32_dpp v18, v57 row_shr:1 row_mask:0xf bank_mask:0xf bound_ctrl:1
	v_mov_b32_dpp v61, v213 row_shl:1 row_mask:0xf bank_mask:0xf bound_ctrl:1
	v_cndmask_b32_e64 v61, v18, v61, s[6:7]
	v_mov_b32_dpp v65, v58 row_shr:2 row_mask:0xf bank_mask:0xf bound_ctrl:1
	v_mov_b32_dpp v18, v58 row_shr:1 row_mask:0xf bank_mask:0xf bound_ctrl:1
	v_mov_b32_dpp v64, v214 row_shl:1 row_mask:0xf bank_mask:0xf bound_ctrl:1
	v_cndmask_b32_e64 v64, v18, v64, s[6:7]
	v_cndmask_b32_e64 v66, v65, v214, s[4:5]
	v_mov_b32_dpp v18, v59 row_shr:1 row_mask:0xf bank_mask:0xf bound_ctrl:1
; __device__ __forceinline__ unsigned cvt_pk_bf16(float lo, float hi) { const bf16x2_t r = __builtin_convertvector((f32x2){lo, hi}, bf16x2_t); return __builtin_bit_cast(unsigned, r); }
; __device__ __forceinline__ float silu_f(float x) { return x * __builtin_amdgcn_rcpf(1.0f + __expf(-x)); }
;     __device__ __forceinline__ void sample(f32x4 (&acc)[2][2][4][2], const Unit& u, int row0t, int wr, int wc, int fr, int fq) const {
;     ...
; #pragma unroll
;             for (int mp = 0; mp < 4; mp += 4) {
;             f32x4 pv[4];
; #pragma unroll
;             for (int k = 0; k < 4; ++k) { pv[k] = (f32x4){0.f, 0.f, 0.f, 0.f}; if (t < 2) pv[k] = *(const f32x4*)((const char*)st + stoff + (unsigned)(((16 * ai + 2 * (mp + k)) * 2 * DFF2 + DFF + 4 * n) * 4)); }
; #pragma unroll
;             for (int k = 0; k < 4; ++k) { const int m = mp + k;
;                 const f32x4 uu = conv4s(acc[ai][1][m][n], pv[k], t, w0, w1, w2, bsv);
;                 const f32x4 ua = acc[ai][0][m][n];
;                 u32x2 w; w.x = cvt_pk_bf16(silu_f(ua[0]) * uu[0], silu_f(ua[1]) * uu[1]); w.y = cvt_pk_bf16(silu_f(ua[2]) * uu[2], silu_f(ua[3]) * uu[3]);
;                 if ((step & 1) == 0) pend[m] = w;
;                 else { u32x4 o; if (n == 1) { o.x = pend[m].x; o.y = pend[m].y; o.z = w.x; o.w = w.y; } else { o.x = w.x; o.y = w.y; o.z = pend[m].x; o.w = pend[m].y; }
;                     *(u32x4*)((char*)act + rowoff0 + (unsigned)((ai * HALF + m * 16) * DFF * 2) + (unsigned)(ca * 2)) = o; }
;                 __builtin_amdgcn_sched_barrier(0);
;             }
	v_mov_b32_dpp v65, v215 row_shl:1 row_mask:0xf bank_mask:0xf bound_ctrl:1
	v_mov_b32_dpp v63, v57 row_shr:2 row_mask:0xf bank_mask:0xf bound_ctrl:1
	v_cndmask_b32_e64 v65, v18, v65, s[6:7]
	v_pk_fma_f32 v[56:57], v[56:57], v[88:89], v[92:93]
	v_mul_f32_e32 v18, 0xbfb8aa3b, v120
	v_pk_fma_f32 v[56:57], v[84:85], v[60:61], v[56:57]
	v_exp_f32_e32 v18, v18
	v_mul_f32_e32 v60, 0xbfb8aa3b, v121
	v_exp_f32_e32 v61, v60
	v_cndmask_b32_e64 v63, v63, v213, s[4:5]
	v_add_f32_e32 v18, 1.0, v18
	v_rcp_f32_e32 v60, v18
	v_add_f32_e32 v18, 1.0, v61
	v_mul_f32_e32 v61, 0xbfb8aa3b, v122
	v_pk_fma_f32 v[56:57], v[68:69], v[62:63], v[56:57]
	v_exp_f32_e32 v62, v61
	v_mul_f32_e32 v61, 0xbfb8aa3b, v123
	v_exp_f32_e32 v63, v61
	s_nop 0
	v_rcp_f32_e32 v61, v18
	v_add_f32_e32 v18, 1.0, v62
	v_mov_b32_dpp v67, v59 row_shr:2 row_mask:0xf bank_mask:0xf bound_ctrl:1
	v_pk_fma_f32 v[58:59], v[58:59], v[90:91], v[94:95]
	v_rcp_f32_e32 v62, v18
	v_add_f32_e32 v18, 1.0, v63
	v_cndmask_b32_e64 v67, v67, v215, s[4:5]
	v_pk_fma_f32 v[58:59], v[86:87], v[64:65], v[58:59]
	v_rcp_f32_e32 v63, v18
	v_pk_fma_f32 v[58:59], v[70:71], v[66:67], v[58:59]
	v_pk_mul_f32 v[60:61], v[120:121], v[60:61]
	s_mov_b32 s2, 0x2c000
	v_pk_mul_f32 v[56:57], v[60:61], v[56:57]
	s_nop 0
	v_cvt_pk_bf16_f32 v108, v56, v57
	v_pk_mul_f32 v[56:57], v[122:123], v[62:63]
	s_nop 0
	v_pk_mul_f32 v[56:57], v[56:57], v[58:59]
	s_nop 0
	v_cvt_pk_bf16_f32 v109, v56, v57
	v_add_co_u32_e32 v56, vcc, s2, v114
	s_nop 1
	v_addc_co_u32_e32 v57, vcc, 0, v115, vcc
	global_store_dwordx4 v[56:57], v[106:109], off
	s_nop 0
	s_nop 0
	s_nop 0
	v_mov_b32_dpp v18, v32 row_shr:1 row_mask:0xf bank_mask:0xf bound_ctrl:1
	v_mov_b32_dpp v57, v32 row_shr:2 row_mask:0xf bank_mask:0xf bound_ctrl:1
	v_mov_b32_dpp v56, v216 row_shl:1 row_mask:0xf bank_mask:0xf bound_ctrl:1
	v_cndmask_b32_e64 v56, v18, v56, s[6:7]
	v_cndmask_b32_e64 v58, v57, v216, s[4:5]
	v_mov_b32_dpp v18, v33 row_shr:1 row_mask:0xf bank_mask:0xf bound_ctrl:1
	v_mov_b32_dpp v57, v217 row_shl:1 row_mask:0xf bank_mask:0xf bound_ctrl:1
	v_cndmask_b32_e64 v57, v18, v57, s[6:7]
	v_mov_b32_dpp v61, v34 row_shr:2 row_mask:0xf bank_mask:0xf bound_ctrl:1
	v_mov_b32_dpp v18, v34 row_shr:1 row_mask:0xf bank_mask:0xf bound_ctrl:1
	v_mov_b32_dpp v60, v218 row_shl:1 row_mask:0xf bank_mask:0xf bound_ctrl:1
	v_cndmask_b32_e64 v60, v18, v60, s[6:7]
	v_cndmask_b32_e64 v62, v61, v218, s[4:5]
	v_mov_b32_dpp v18, v35 row_shr:1 row_mask:0xf bank_mask:0xf bound_ctrl:1
	v_mov_b32_dpp v61, v219 row_shl:1 row_mask:0xf bank_mask:0xf bound_ctrl:1
	v_mov_b32_dpp v59, v33 row_shr:2 row_mask:0xf bank_mask:0xf bound_ctrl:1
	v_cndmask_b32_e64 v61, v18, v61, s[6:7]
	v_pk_fma_f32 v[32:33], v[32:33], v[88:89], v[92:93]
	v_mul_f32_e32 v18, 0xbfb8aa3b, v116
	v_pk_fma_f32 v[32:33], v[84:85], v[56:57], v[32:33]
	v_exp_f32_e32 v18, v18
	v_mul_f32_e32 v56, 0xbfb8aa3b, v117
	v_exp_f32_e32 v57, v56
	v_cndmask_b32_e64 v59, v59, v217, s[4:5]
	v_add_f32_e32 v18, 1.0, v18
	v_rcp_f32_e32 v56, v18
	v_add_f32_e32 v18, 1.0, v57
	v_mul_f32_e32 v57, 0xbfb8aa3b, v118
	v_pk_fma_f32 v[32:33], v[68:69], v[58:59], v[32:33]
	v_exp_f32_e32 v58, v57
	v_mul_f32_e32 v57, 0xbfb8aa3b, v119
	v_exp_f32_e32 v59, v57
	s_nop 0
	v_rcp_f32_e32 v57, v18
	v_add_f32_e32 v18, 1.0, v58
	v_mov_b32_dpp v63, v35 row_shr:2 row_mask:0xf bank_mask:0xf bound_ctrl:1
	v_pk_fma_f32 v[34:35], v[34:35], v[90:91], v[94:95]
	v_rcp_f32_e32 v58, v18
	v_add_f32_e32 v18, 1.0, v59
	v_cndmask_b32_e64 v63, v63, v219, s[4:5]
	v_pk_fma_f32 v[34:35], v[86:87], v[60:61], v[34:35]
	v_rcp_f32_e32 v59, v18
	v_pk_fma_f32 v[34:35], v[70:71], v[62:63], v[34:35]
	v_pk_mul_f32 v[56:57], v[116:117], v[56:57]
	s_nop 0
	v_pk_mul_f32 v[32:33], v[56:57], v[32:33]
	s_nop 0
	v_cvt_pk_bf16_f32 v104, v32, v33
	v_pk_mul_f32 v[32:33], v[118:119], v[58:59]
	s_nop 0
	v_pk_mul_f32 v[32:33], v[32:33], v[34:35]
	s_nop 0
	v_cvt_pk_bf16_f32 v105, v32, v33
	v_add_co_u32_e32 v32, vcc, 0x42000, v114
	s_nop 1
	v_addc_co_u32_e32 v33, vcc, 0, v115, vcc
	global_store_dwordx4 v[32:33], v[102:105], off
	v_mov_b32_e32 v56, 0
	v_mov_b32_e32 v64, 0
	v_mov_b32_e32 v65, 0
	v_mov_b32_e32 v66, 0
	v_mov_b32_e32 v67, 0
	v_mov_b32_e32 v57, 0
	v_mov_b32_e32 v58, 0
	v_mov_b32_e32 v59, 0
	v_mov_b32_e32 v32, 0
	v_mov_b32_e32 v60, 0
	v_mov_b32_e32 v61, 0
	v_mov_b32_e32 v62, 0
	v_mov_b32_e32 v63, 0
	v_mov_b32_e32 v33, 0
	v_mov_b32_e32 v34, 0
	v_mov_b32_e32 v35, 0
	s_nop 0
	s_nop 0
	v_mov_b32_e32 v100, v19
	v_mov_b32_dpp v18, v52 row_shr:1 row_mask:0xf bank_mask:0xf bound_ctrl:1
	v_mov_b32_dpp v101, v52 row_shr:2 row_mask:0xf bank_mask:0xf bound_ctrl:1
	v_mov_b32_e32 v204, 0
	v_mov_b32_e32 v205, 0
	v_mov_b32_e32 v206, 0
	v_mov_b32_e32 v207, 0
	v_mov_b32_e32 v208, 0
	v_mov_b32_e32 v209, 0
	v_mov_b32_e32 v210, 0
	v_mov_b32_e32 v211, 0
	v_mov_b32_e32 v212, 0
	v_mov_b32_e32 v213, 0
	v_mov_b32_e32 v214, 0
	v_mov_b32_e32 v215, 0
	v_mov_b32_e32 v216, 0
	v_mov_b32_e32 v217, 0
	v_mov_b32_e32 v218, 0
	v_mov_b32_e32 v219, 0
	s_waitcnt vmcnt(0)
	s_and_saveexec_b64 s[100:101], s[4:5]
	s_cbranch_execz .Lspp_7
	s_mov_b64 s[98:99], 0xb2c00
	v_lshl_add_u64 v[194:195], v[172:173], 0, s[98:99]
	global_load_dwordx4 v[204:207], v[194:195], off
	s_mov_b64 s[98:99], 0xc8c00
	v_lshl_add_u64 v[194:195], v[172:173], 0, s[98:99]
	global_load_dwordx4 v[208:211], v[194:195], off
	s_mov_b64 s[98:99], 0xdec00
	v_lshl_add_u64 v[194:195], v[172:173], 0, s[98:99]
	global_load_dwordx4 v[212:215], v[194:195], off
	s_mov_b64 s[98:99], 0xf4c00
	v_lshl_add_u64 v[194:195], v[172:173], 0, s[98:99]
	global_load_dwordx4 v[216:219], v[194:195], off
;     __device__ __forceinline__ f32x4 conv4s(const f32x4 c4, const f32x4 pv, int t, const f32x4 w0, const f32x4 w1, const f32x4 w2, const f32x4 bsv) const {
;         f32x4 p1, p2;
; #pragma unroll
;         for (int e = 0; e < 4; ++e) { p1[e] = dpp_f<0x111>(0.f, c4[e]); p2[e] = dpp_f<0x112>(0.f, c4[e]); const float q1 = dpp_f<0x101>(0.f, pv[e]);
;             p1[e] = t == 0 ? q1 : p1[e]; p2[e] = t < 2 ? pv[e] : p2[e]; }
;         f32x4 uu = bsv + w2 * c4 + w1 * p1 + w0 * p2;
;         asm volatile("" : "+v"(uu));
;         return uu;
;     }
;     __device__ __forceinline__ void sample(f32x4 (&acc)[2][2][4][2], const Unit& u, int row0t, int wr, int wc, int fr, int fq) const {
;     ...
; #pragma unroll
;             for (int mp = 0; mp < 4; mp += 4) {
;             f32x4 pv[4];
; #pragma unroll
;             for (int k = 0; k < 4; ++k) { pv[k] = (f32x4){0.f, 0.f, 0.f, 0.f}; if (t < 2) pv[k] = *(const f32x4*)((const char*)st + stoff + (unsigned)(((16 * ai + 2 * (mp + k)) * 2 * DFF2 + DFF + 4 * n) * 4)); }
; #pragma unroll
;             for (int k = 0; k < 4; ++k) { const int m = mp + k;
;                 const f32x4 uu = conv4s(acc[ai][1][m][n], pv[k], t, w0, w1, w2, bsv);
;                 const f32x4 ua = acc[ai][0][m][n];
.Lspp_7:
	s_or_b64 exec, exec, s[100:101]
	s_nop 4
	v_mov_b32_dpp v100, v178 row_shl:1 row_mask:0xf bank_mask:0xf
	v_cndmask_b32_e64 v100, v18, v100, s[6:7]
	v_cndmask_b32_e64 v64, v101, v178, s[4:5]
	s_nop 0
	s_nop 0
	v_mov_b32_dpp v18, v53 row_shr:1 row_mask:0xf bank_mask:0xf bound_ctrl:1
	v_mov_b32_dpp v102, v53 row_shr:2 row_mask:0xf bank_mask:0xf bound_ctrl:1
	v_mov_b32_dpp v101, v179 row_shl:1 row_mask:0xf bank_mask:0xf bound_ctrl:1
	v_cndmask_b32_e64 v101, v18, v101, s[6:7]
	v_cndmask_b32_e64 v65, v102, v179, s[4:5]
	v_mov_b32_dpp v18, v54 row_shr:1 row_mask:0xf bank_mask:0xf bound_ctrl:1
	v_mov_b32_dpp v103, v54 row_shr:2 row_mask:0xf bank_mask:0xf bound_ctrl:1
	v_mov_b32_dpp v102, v180 row_shl:1 row_mask:0xf bank_mask:0xf bound_ctrl:1
	v_cndmask_b32_e64 v102, v18, v102, s[6:7]
	v_cndmask_b32_e64 v66, v103, v180, s[4:5]
	v_mov_b32_dpp v18, v55 row_shr:1 row_mask:0xf bank_mask:0xf bound_ctrl:1
	v_mov_b32_dpp v103, v181 row_shl:1 row_mask:0xf bank_mask:0xf bound_ctrl:1
	v_mov_b32_dpp v104, v55 row_shr:2 row_mask:0xf bank_mask:0xf bound_ctrl:1
	v_cndmask_b32_e64 v103, v18, v103, s[6:7]
	v_pk_fma_f32 v[54:55], v[54:55], v[90:91], v[94:95]
	v_pk_fma_f32 v[52:53], v[52:53], v[88:89], v[92:93]
	v_cndmask_b32_e64 v67, v104, v181, s[4:5]
	v_pk_fma_f32 v[54:55], v[86:87], v[102:103], v[54:55]
	v_pk_fma_f32 v[52:53], v[84:85], v[100:101], v[52:53]
	v_mov_b32_e32 v171, v19
	v_pk_fma_f32 v[102:103], v[70:71], v[66:67], v[54:55]
	v_pk_fma_f32 v[100:101], v[68:69], v[64:65], v[52:53]
	v_lshl_add_u64 v[112:113], s[96:97], 0, v[170:171]
	v_lshl_add_u64 v[116:117], s[0:1], 0, v[170:171]
	v_lshl_add_u64 v[118:119], s[8:9], 0, v[170:171]
	v_lshl_add_u64 v[120:121], s[66:67], 0, v[170:171]
	v_mov_b32_dpp v18, v48 row_shr:1 row_mask:0xf bank_mask:0xf bound_ctrl:1
	v_mov_b32_dpp v53, v48 row_shr:2 row_mask:0xf bank_mask:0xf bound_ctrl:1
	v_mov_b32_dpp v52, v182 row_shl:1 row_mask:0xf bank_mask:0xf bound_ctrl:1
	v_cndmask_b32_e64 v52, v18, v52, s[6:7]
	v_cndmask_b32_e64 v54, v53, v182, s[4:5]
	v_mov_b32_dpp v18, v49 row_shr:1 row_mask:0xf bank_mask:0xf bound_ctrl:1
	v_mov_b32_dpp v55, v49 row_shr:2 row_mask:0xf bank_mask:0xf bound_ctrl:1
	v_mov_b32_dpp v53, v183 row_shl:1 row_mask:0xf bank_mask:0xf bound_ctrl:1
	v_cndmask_b32_e64 v53, v18, v53, s[6:7]
	v_cndmask_b32_e64 v55, v55, v183, s[4:5]
	v_mov_b32_dpp v18, v50 row_shr:1 row_mask:0xf bank_mask:0xf bound_ctrl:1
	v_mov_b32_dpp v57, v50 row_shr:2 row_mask:0xf bank_mask:0xf bound_ctrl:1
	v_mov_b32_dpp v56, v184 row_shl:1 row_mask:0xf bank_mask:0xf bound_ctrl:1
	v_cndmask_b32_e64 v56, v18, v56, s[6:7]
	v_cndmask_b32_e64 v58, v57, v184, s[4:5]
	v_mov_b32_dpp v18, v51 row_shr:1 row_mask:0xf bank_mask:0xf bound_ctrl:1
	v_mov_b32_dpp v57, v185 row_shl:1 row_mask:0xf bank_mask:0xf bound_ctrl:1
	v_mov_b32_dpp v64, v51 row_shr:2 row_mask:0xf bank_mask:0xf bound_ctrl:1
	v_cndmask_b32_e64 v57, v18, v57, s[6:7]
	v_pk_fma_f32 v[50:51], v[50:51], v[90:91], v[94:95]
	v_pk_fma_f32 v[48:49], v[48:49], v[88:89], v[92:93]
	v_cndmask_b32_e64 v59, v64, v185, s[4:5]
	v_pk_fma_f32 v[50:51], v[86:87], v[56:57], v[50:51]
	v_pk_fma_f32 v[48:49], v[84:85], v[52:53], v[48:49]
	v_pk_fma_f32 v[106:107], v[70:71], v[58:59], v[50:51]
	v_pk_fma_f32 v[104:105], v[68:69], v[54:55], v[48:49]
	s_nop 0
	v_mov_b32_dpp v18, v44 row_shr:1 row_mask:0xf bank_mask:0xf bound_ctrl:1
	v_mov_b32_dpp v49, v44 row_shr:2 row_mask:0xf bank_mask:0xf bound_ctrl:1
	v_mov_b32_dpp v48, v186 row_shl:1 row_mask:0xf bank_mask:0xf bound_ctrl:1
	v_cndmask_b32_e64 v48, v18, v48, s[6:7]
	v_cndmask_b32_e64 v50, v49, v186, s[4:5]
	v_mov_b32_dpp v18, v45 row_shr:1 row_mask:0xf bank_mask:0xf bound_ctrl:1
	v_mov_b32_dpp v49, v187 row_shl:1 row_mask:0xf bank_mask:0xf bound_ctrl:1
	v_cndmask_b32_e64 v49, v18, v49, s[6:7]
	v_mov_b32_dpp v53, v46 row_shr:2 row_mask:0xf bank_mask:0xf bound_ctrl:1
	v_mov_b32_dpp v18, v46 row_shr:1 row_mask:0xf bank_mask:0xf bound_ctrl:1
	v_mov_b32_dpp v52, v188 row_shl:1 row_mask:0xf bank_mask:0xf bound_ctrl:1
	v_cndmask_b32_e64 v52, v18, v52, s[6:7]
	v_cndmask_b32_e64 v54, v53, v188, s[4:5]
	v_mov_b32_dpp v18, v47 row_shr:1 row_mask:0xf bank_mask:0xf bound_ctrl:1
	v_mov_b32_dpp v53, v189 row_shl:1 row_mask:0xf bank_mask:0xf bound_ctrl:1
	v_mov_b32_dpp v51, v45 row_shr:2 row_mask:0xf bank_mask:0xf bound_ctrl:1
	v_mov_b32_dpp v55, v47 row_shr:2 row_mask:0xf bank_mask:0xf bound_ctrl:1
	v_cndmask_b32_e64 v53, v18, v53, s[6:7]
	v_pk_fma_f32 v[46:47], v[46:47], v[90:91], v[94:95]
	v_pk_fma_f32 v[44:45], v[44:45], v[88:89], v[92:93]
	v_cndmask_b32_e64 v51, v51, v187, s[4:5]
	v_cndmask_b32_e64 v55, v55, v189, s[4:5]
	v_pk_fma_f32 v[46:47], v[86:87], v[52:53], v[46:47]
	v_pk_fma_f32 v[44:45], v[84:85], v[48:49], v[44:45]
	v_pk_fma_f32 v[110:111], v[70:71], v[54:55], v[46:47]
	v_pk_fma_f32 v[108:109], v[68:69], v[50:51], v[44:45]
	s_nop 0
	v_mov_b32_dpp v18, v20 row_shr:1 row_mask:0xf bank_mask:0xf bound_ctrl:1
	v_mov_b32_dpp v45, v20 row_shr:2 row_mask:0xf bank_mask:0xf bound_ctrl:1
	v_mov_b32_dpp v44, v190 row_shl:1 row_mask:0xf bank_mask:0xf bound_ctrl:1
	v_cndmask_b32_e64 v44, v18, v44, s[6:7]
	v_cndmask_b32_e64 v32, v45, v190, s[4:5]
	v_mov_b32_dpp v18, v21 row_shr:1 row_mask:0xf bank_mask:0xf bound_ctrl:1
	v_mov_b32_dpp v46, v21 row_shr:2 row_mask:0xf bank_mask:0xf bound_ctrl:1
	v_mov_b32_dpp v45, v191 row_shl:1 row_mask:0xf bank_mask:0xf bound_ctrl:1
	v_cndmask_b32_e64 v45, v18, v45, s[6:7]
	v_cndmask_b32_e64 v33, v46, v191, s[4:5]
	v_mov_b32_dpp v18, v22 row_shr:1 row_mask:0xf bank_mask:0xf bound_ctrl:1
	v_mov_b32_dpp v47, v22 row_shr:2 row_mask:0xf bank_mask:0xf bound_ctrl:1
	v_mov_b32_dpp v46, v192 row_shl:1 row_mask:0xf bank_mask:0xf bound_ctrl:1
; __device__ __forceinline__ unsigned cvt_pk_bf16(float lo, float hi) { const bf16x2_t r = __builtin_convertvector((f32x2){lo, hi}, bf16x2_t); return __builtin_bit_cast(unsigned, r); }
; __device__ __forceinline__ float silu_f(float x) { return x * __builtin_amdgcn_rcpf(1.0f + __expf(-x)); }
;     __device__ __forceinline__ void sample(f32x4 (&acc)[2][2][4][2], const Unit& u, int row0t, int wr, int wc, int fr, int fq) const {
;     ...
;         for (int step = 0; step < 4; ++step) {
;             const int n = (step == 1 || step == 2) ? 1 : 0, ai = step >> 1;
;             f32x4 w0, w1, w2, bsv;
;             if (step != 2) { const unsigned cso = (unsigned)((DFF + ca + 4 * n) * 4);
;                 w0 = *(const f32x4*)((const char*)cw + cso); w1 = *(const f32x4*)((const char*)(cw + DFF2) + cso); w2 = *(const f32x4*)((const char*)(cw + 2 * DFF2) + cso); bsv = *(const f32x4*)((const char*)cb + cso);
;                 wk[0] = w0; wk[1] = w1; wk[2] = w2; wk[3] = bsv; }
;             else { w0 = wk[0]; w1 = wk[1]; w2 = wk[2]; bsv = wk[3]; }
; #pragma unroll
;             for (int mp = 0; mp < 4; mp += 4) {
;             f32x4 pv[4];
; #pragma unroll
;             for (int k = 0; k < 4; ++k) { pv[k] = (f32x4){0.f, 0.f, 0.f, 0.f}; if (t < 2) pv[k] = *(const f32x4*)((const char*)st + stoff + (unsigned)(((16 * ai + 2 * (mp + k)) * 2 * DFF2 + DFF + 4 * n) * 4)); }
; #pragma unroll
;             for (int k = 0; k < 4; ++k) { const int m = mp + k;
;                 const f32x4 uu = conv4s(acc[ai][1][m][n], pv[k], t, w0, w1, w2, bsv);
;                 const f32x4 ua = acc[ai][0][m][n];
;                 u32x2 w; w.x = cvt_pk_bf16(silu_f(ua[0]) * uu[0], silu_f(ua[1]) * uu[1]); w.y = cvt_pk_bf16(silu_f(ua[2]) * uu[2], silu_f(ua[3]) * uu[3]);
;                 if ((step & 1) == 0) pend[m] = w;
;                 else { u32x4 o; if (n == 1) { o.x = pend[m].x; o.y = pend[m].y; o.z = w.x; o.w = w.y; } else { o.x = w.x; o.y = w.y; o.z = pend[m].x; o.w = pend[m].y; }
;                     *(u32x4*)((char*)act + rowoff0 + (unsigned)((ai * HALF + m * 16) * DFF * 2) + (unsigned)(ca * 2)) = o; }
;                 __builtin_amdgcn_sched_barrier(0);
;             }
	v_cndmask_b32_e64 v46, v18, v46, s[6:7]
	v_cndmask_b32_e64 v34, v47, v192, s[4:5]
	v_mov_b32_dpp v18, v23 row_shr:1 row_mask:0xf bank_mask:0xf bound_ctrl:1
	v_mov_b32_dpp v47, v193 row_shl:1 row_mask:0xf bank_mask:0xf bound_ctrl:1
	v_mov_b32_dpp v48, v23 row_shr:2 row_mask:0xf bank_mask:0xf bound_ctrl:1
	v_cndmask_b32_e64 v47, v18, v47, s[6:7]
	v_pk_fma_f32 v[22:23], v[22:23], v[90:91], v[94:95]
	v_pk_fma_f32 v[20:21], v[20:21], v[88:89], v[92:93]
	v_cndmask_b32_e64 v35, v48, v193, s[4:5]
	v_pk_fma_f32 v[22:23], v[86:87], v[46:47], v[22:23]
	v_pk_fma_f32 v[20:21], v[84:85], v[44:45], v[20:21]
	v_pk_fma_f32 v[86:87], v[70:71], v[34:35], v[22:23]
	v_pk_fma_f32 v[84:85], v[68:69], v[32:33], v[20:21]
	s_nop 0
	global_load_dwordx4 v[20:23], v[112:113], off
	global_load_dwordx4 v[32:35], v[116:117], off
	global_load_dwordx4 v[44:47], v[118:119], off
	global_load_dwordx4 v[48:51], v[120:121], off
	v_mov_b32_e32 v62, 0
	v_mov_b32_e32 v68, 0
	v_mov_b32_e32 v69, 0
	v_mov_b32_e32 v70, 0
	v_mov_b32_e32 v71, 0
	v_mov_b32_e32 v63, 0
	v_mov_b32_e32 v64, 0
	v_mov_b32_e32 v65, 0
	v_writelane_b32 v244, s50, 58
	s_nop 1
	v_writelane_b32 v244, s51, 59
	v_mov_b32_e32 v52, 0
	v_mov_b32_e32 v58, 0
	v_mov_b32_e32 v59, 0
	v_mov_b32_e32 v60, 0
	v_mov_b32_e32 v61, 0
	v_mov_b32_e32 v53, 0
	v_mov_b32_e32 v54, 0
	v_mov_b32_e32 v55, 0
	v_mul_f32_e32 v18, 0xbfb8aa3b, v96
	v_exp_f32_e32 v18, v18
	s_mov_b32 s0, 0xb0000
	v_add_f32_e32 v18, 1.0, v18
	v_rcp_f32_e32 v56, v18
	v_mul_f32_e32 v18, 0xbfb8aa3b, v97
	v_exp_f32_e32 v18, v18
	s_nop 0
	v_add_f32_e32 v18, 1.0, v18
	v_rcp_f32_e32 v57, v18
	v_mul_f32_e32 v18, 0xbfb8aa3b, v98
	v_exp_f32_e32 v18, v18
	v_pk_mul_f32 v[56:57], v[96:97], v[56:57]
	s_nop 0
	v_pk_mul_f32 v[56:57], v[56:57], v[84:85]
	v_add_f32_e32 v18, 1.0, v18
	v_rcp_f32_e32 v66, v18
	v_mul_f32_e32 v18, 0xbfb8aa3b, v99
	v_exp_f32_e32 v18, v18
	v_cvt_pk_bf16_f32 v56, v56, v57
	v_add_f32_e32 v18, 1.0, v18
	v_rcp_f32_e32 v67, v18
	v_mul_f32_e32 v18, 0xbfb8aa3b, v80
	v_exp_f32_e32 v18, v18
	v_pk_mul_f32 v[66:67], v[98:99], v[66:67]
	s_nop 0
	v_pk_mul_f32 v[66:67], v[66:67], v[86:87]
	v_add_f32_e32 v18, 1.0, v18
	v_cvt_pk_bf16_f32 v57, v66, v67
	v_rcp_f32_e32 v66, v18
	v_mul_f32_e32 v18, 0xbfb8aa3b, v81
	v_exp_f32_e32 v18, v18
	s_nop 0
	v_add_f32_e32 v18, 1.0, v18
	v_rcp_f32_e32 v67, v18
	v_mul_f32_e32 v18, 0xbfb8aa3b, v82
	v_exp_f32_e32 v18, v18
	v_pk_mul_f32 v[66:67], v[80:81], v[66:67]
	s_nop 0
	v_pk_mul_f32 v[66:67], v[66:67], v[108:109]
	v_add_f32_e32 v18, 1.0, v18
	v_rcp_f32_e32 v80, v18
	v_mul_f32_e32 v18, 0xbfb8aa3b, v83
	v_exp_f32_e32 v18, v18
	v_cvt_pk_bf16_f32 v66, v66, v67
	v_add_f32_e32 v18, 1.0, v18
	v_rcp_f32_e32 v81, v18
	v_mul_f32_e32 v18, 0xbfb8aa3b, v76
	v_exp_f32_e32 v18, v18
	v_pk_mul_f32 v[80:81], v[82:83], v[80:81]
	s_nop 0
	v_pk_mul_f32 v[80:81], v[80:81], v[110:111]
	v_add_f32_e32 v18, 1.0, v18
	v_cvt_pk_bf16_f32 v67, v80, v81
	v_rcp_f32_e32 v80, v18
	v_mul_f32_e32 v18, 0xbfb8aa3b, v77
	v_exp_f32_e32 v18, v18
	s_nop 0
	v_add_f32_e32 v18, 1.0, v18
	v_rcp_f32_e32 v81, v18
	v_mul_f32_e32 v18, 0xbfb8aa3b, v78
	v_exp_f32_e32 v18, v18
	v_pk_mul_f32 v[76:77], v[76:77], v[80:81]
	s_nop 0
	v_pk_mul_f32 v[76:77], v[76:77], v[104:105]
	v_add_f32_e32 v18, 1.0, v18
	v_rcp_f32_e32 v80, v18
	v_mul_f32_e32 v18, 0xbfb8aa3b, v79
	v_exp_f32_e32 v18, v18
	v_cvt_pk_bf16_f32 v76, v76, v77
	v_add_f32_e32 v18, 1.0, v18
	v_rcp_f32_e32 v81, v18
	v_mul_f32_e32 v18, 0xbfb8aa3b, v72
	v_exp_f32_e32 v18, v18
	v_pk_mul_f32 v[78:79], v[78:79], v[80:81]
	s_nop 0
	v_pk_mul_f32 v[78:79], v[78:79], v[106:107]
	v_add_f32_e32 v18, 1.0, v18
	v_cvt_pk_bf16_f32 v77, v78, v79
	v_rcp_f32_e32 v78, v18
	v_mul_f32_e32 v18, 0xbfb8aa3b, v73
	v_exp_f32_e32 v18, v18
	s_nop 0
	v_add_f32_e32 v18, 1.0, v18
	v_rcp_f32_e32 v79, v18
	v_mul_f32_e32 v18, 0xbfb8aa3b, v74
	v_exp_f32_e32 v18, v18
	v_mov_b32_dpp v80, v17 row_shr:2 row_mask:0xf bank_mask:0xf bound_ctrl:1
	v_pk_mul_f32 v[72:73], v[72:73], v[78:79]
	v_add_f32_e32 v18, 1.0, v18
	v_rcp_f32_e32 v78, v18
	v_mul_f32_e32 v18, 0xbfb8aa3b, v75
	v_exp_f32_e32 v18, v18
	v_pk_mul_f32 v[72:73], v[72:73], v[100:101]
	v_add_f32_e32 v18, 1.0, v18
	v_rcp_f32_e32 v79, v18
	v_cvt_pk_bf16_f32 v72, v72, v73
	s_nop 0
	v_pk_mul_f32 v[74:75], v[74:75], v[78:79]
	s_nop 0
	v_pk_mul_f32 v[74:75], v[74:75], v[102:103]
	v_mov_b32_dpp v18, v14 row_shr:1 row_mask:0xf bank_mask:0xf bound_ctrl:1
	v_cvt_pk_bf16_f32 v73, v74, v75
	s_nop 0
	s_nop 0
	s_nop 0
	v_mov_b32_dpp v75, v14 row_shr:2 row_mask:0xf bank_mask:0xf bound_ctrl:1
	s_waitcnt vmcnt(0)
; __device__ __forceinline__ unsigned cvt_pk_bf16(float lo, float hi) { const bf16x2_t r = __builtin_convertvector((f32x2){lo, hi}, bf16x2_t); return __builtin_bit_cast(unsigned, r); }
; __device__ __forceinline__ float silu_f(float x) { return x * __builtin_amdgcn_rcpf(1.0f + __expf(-x)); }
;     __device__ __forceinline__ void sample(f32x4 (&acc)[2][2][4][2], const Unit& u, int row0t, int wr, int wc, int fr, int fq) const {
;     ...
; #pragma unroll
;             for (int mp = 0; mp < 4; mp += 4) {
;             f32x4 pv[4];
; #pragma unroll
;             for (int k = 0; k < 4; ++k) { pv[k] = (f32x4){0.f, 0.f, 0.f, 0.f}; if (t < 2) pv[k] = *(const f32x4*)((const char*)st + stoff + (unsigned)(((16 * ai + 2 * (mp + k)) * 2 * DFF2 + DFF + 4 * n) * 4)); }
; #pragma unroll
;             for (int k = 0; k < 4; ++k) { const int m = mp + k;
;                 const f32x4 uu = conv4s(acc[ai][1][m][n], pv[k], t, w0, w1, w2, bsv);
;                 const f32x4 ua = acc[ai][0][m][n];
;                 u32x2 w; w.x = cvt_pk_bf16(silu_f(ua[0]) * uu[0], silu_f(ua[1]) * uu[1]); w.y = cvt_pk_bf16(silu_f(ua[2]) * uu[2], silu_f(ua[3]) * uu[3]);
;                 if ((step & 1) == 0) pend[m] = w;
;                 else { u32x4 o; if (n == 1) { o.x = pend[m].x; o.y = pend[m].y; o.z = w.x; o.w = w.y; } else { o.x = w.x; o.y = w.y; o.z = pend[m].x; o.w = pend[m].y; }
;                     *(u32x4*)((char*)act + rowoff0 + (unsigned)((ai * HALF + m * 16) * DFF * 2) + (unsigned)(ca * 2)) = o; }
;                 __builtin_amdgcn_sched_barrier(0);
;             }
	v_mov_b32_dpp v74, v204 row_shl:1 row_mask:0xf bank_mask:0xf bound_ctrl:1
	v_cndmask_b32_e64 v74, v18, v74, s[6:7]
	v_cndmask_b32_e64 v68, v75, v204, s[4:5]
	s_nop 0
	s_nop 0
	v_mov_b32_dpp v78, v15 row_shr:2 row_mask:0xf bank_mask:0xf bound_ctrl:1
	v_mov_b32_dpp v18, v15 row_shr:1 row_mask:0xf bank_mask:0xf bound_ctrl:1
	v_mov_b32_dpp v75, v205 row_shl:1 row_mask:0xf bank_mask:0xf bound_ctrl:1
	v_cndmask_b32_e64 v75, v18, v75, s[6:7]
	v_cndmask_b32_e64 v69, v78, v205, s[4:5]
	v_mov_b32_dpp v18, v16 row_shr:1 row_mask:0xf bank_mask:0xf bound_ctrl:1
	v_mov_b32_dpp v79, v16 row_shr:2 row_mask:0xf bank_mask:0xf bound_ctrl:1
	v_mov_b32_dpp v78, v206 row_shl:1 row_mask:0xf bank_mask:0xf bound_ctrl:1
	v_cndmask_b32_e64 v78, v18, v78, s[6:7]
	v_cndmask_b32_e64 v70, v79, v206, s[4:5]
	s_nop 0
	v_pk_fma_f32 v[14:15], v[14:15], v[44:45], v[48:49]
	v_mov_b32_dpp v18, v17 row_shr:1 row_mask:0xf bank_mask:0xf bound_ctrl:1
	v_mov_b32_dpp v79, v207 row_shl:1 row_mask:0xf bank_mask:0xf bound_ctrl:1
	v_cndmask_b32_e64 v79, v18, v79, s[6:7]
	v_mul_f32_e32 v18, 0xbfb8aa3b, v40
	v_exp_f32_e32 v18, v18
	v_pk_fma_f32 v[14:15], v[32:33], v[74:75], v[14:15]
	v_pk_fma_f32 v[16:17], v[16:17], v[46:47], v[50:51]
	v_pk_fma_f32 v[14:15], v[20:21], v[68:69], v[14:15]
	v_add_f32_e32 v18, 1.0, v18
	v_rcp_f32_e32 v68, v18
	v_mul_f32_e32 v18, 0xbfb8aa3b, v41
	v_exp_f32_e32 v18, v18
	v_cndmask_b32_e64 v71, v80, v207, s[4:5]
	v_pk_fma_f32 v[16:17], v[34:35], v[78:79], v[16:17]
	v_add_f32_e32 v18, 1.0, v18
	v_rcp_f32_e32 v69, v18
	v_pk_fma_f32 v[16:17], v[22:23], v[70:71], v[16:17]
	v_pk_mul_f32 v[40:41], v[40:41], v[68:69]
	s_nop 0
	v_pk_mul_f32 v[14:15], v[40:41], v[14:15]
	s_nop 0
	v_cvt_pk_bf16_f32 v70, v14, v15
	v_mul_f32_e32 v14, 0xbfb8aa3b, v42
	v_mul_f32_e32 v15, 0xbfb8aa3b, v43
	v_exp_f32_e32 v14, v14
	v_exp_f32_e32 v15, v15
	v_add_f32_e32 v14, 1.0, v14
	v_add_f32_e32 v15, 1.0, v15
	v_rcp_f32_e32 v14, v14
	v_rcp_f32_e32 v15, v15
	s_nop 0
	v_pk_mul_f32 v[14:15], v[42:43], v[14:15]
	s_nop 0
	v_pk_mul_f32 v[14:15], v[14:15], v[16:17]
	s_nop 0
	v_cvt_pk_bf16_f32 v71, v14, v15
	v_add_co_u32_e32 v14, vcc, s0, v114
	s_nop 1
	v_addc_co_u32_e32 v15, vcc, 0, v115, vcc
	global_store_dwordx4 v[14:15], v[70:73], off
	s_nop 0
	s_nop 0
	s_nop 0
	v_mov_b32_dpp v14, v10 row_shr:1 row_mask:0xf bank_mask:0xf bound_ctrl:1
	v_mov_b32_dpp v15, v10 row_shr:2 row_mask:0xf bank_mask:0xf bound_ctrl:1
	v_mov_b32_dpp v16, v208 row_shl:1 row_mask:0xf bank_mask:0xf bound_ctrl:1
	v_cndmask_b32_e64 v14, v14, v16, s[6:7]
	v_cndmask_b32_e64 v16, v15, v208, s[4:5]
	v_mov_b32_dpp v15, v11 row_shr:1 row_mask:0xf bank_mask:0xf bound_ctrl:1
	v_mov_b32_dpp v18, v209 row_shl:1 row_mask:0xf bank_mask:0xf bound_ctrl:1
	v_mov_b32_dpp v17, v11 row_shr:2 row_mask:0xf bank_mask:0xf bound_ctrl:1
	v_cndmask_b32_e64 v15, v15, v18, s[6:7]
	v_pk_fma_f32 v[10:11], v[10:11], v[44:45], v[48:49]
	v_cndmask_b32_e64 v17, v17, v209, s[4:5]
	v_pk_fma_f32 v[10:11], v[32:33], v[14:15], v[10:11]
	v_mul_f32_e32 v14, 0xbfb8aa3b, v36
	v_mul_f32_e32 v15, 0xbfb8aa3b, v37
	v_exp_f32_e32 v14, v14
	v_exp_f32_e32 v15, v15
	v_pk_fma_f32 v[10:11], v[20:21], v[16:17], v[10:11]
	v_mul_f32_e32 v16, 0xbfb8aa3b, v38
	v_mul_f32_e32 v17, 0xbfb8aa3b, v39
	s_nop 0
	s_nop 0
	s_nop 0
	v_exp_f32_e32 v16, v16
	v_exp_f32_e32 v17, v17
	v_mov_b32_dpp v18, v12 row_shr:1 row_mask:0xf bank_mask:0xf bound_ctrl:1
	v_mov_b32_dpp v41, v12 row_shr:2 row_mask:0xf bank_mask:0xf bound_ctrl:1
	v_mov_b32_dpp v40, v210 row_shl:1 row_mask:0xf bank_mask:0xf bound_ctrl:1
	v_cndmask_b32_e64 v40, v18, v40, s[6:7]
	v_cndmask_b32_e64 v42, v41, v210, s[4:5]
	s_nop 0
	s_nop 0
	v_add_f32_e32 v14, 1.0, v14
	v_add_f32_e32 v15, 1.0, v15
	v_mov_b32_dpp v18, v13 row_shr:1 row_mask:0xf bank_mask:0xf bound_ctrl:1
	s_nop 0
	v_mov_b32_dpp v41, v211 row_shl:1 row_mask:0xf bank_mask:0xf bound_ctrl:1
	v_rcp_f32_e32 v14, v14
	v_rcp_f32_e32 v15, v15
	v_mov_b32_dpp v43, v13 row_shr:2 row_mask:0xf bank_mask:0xf bound_ctrl:1
	v_cndmask_b32_e64 v41, v18, v41, s[6:7]
	v_pk_fma_f32 v[12:13], v[12:13], v[46:47], v[50:51]
	v_add_f32_e32 v16, 1.0, v16
	v_add_f32_e32 v17, 1.0, v17
	v_cndmask_b32_e64 v43, v43, v211, s[4:5]
	v_pk_fma_f32 v[12:13], v[34:35], v[40:41], v[12:13]
	v_rcp_f32_e32 v16, v16
	v_rcp_f32_e32 v17, v17
	v_pk_fma_f32 v[12:13], v[22:23], v[42:43], v[12:13]
	v_pk_mul_f32 v[14:15], v[36:37], v[14:15]
	s_mov_b32 s0, 0xc6000
	v_pk_mul_f32 v[10:11], v[14:15], v[10:11]
	s_nop 0
	v_cvt_pk_bf16_f32 v74, v10, v11
	v_pk_mul_f32 v[10:11], v[38:39], v[16:17]
	s_nop 0
	v_pk_mul_f32 v[10:11], v[10:11], v[12:13]
	s_nop 0
	v_cvt_pk_bf16_f32 v75, v10, v11
	v_add_co_u32_e32 v10, vcc, s0, v114
	s_nop 1
	v_addc_co_u32_e32 v11, vcc, 0, v115, vcc
	global_store_dwordx4 v[10:11], v[74:77], off
	s_nop 0
	s_nop 0
	s_nop 0
	v_mov_b32_dpp v10, v6 row_shr:1 row_mask:0xf bank_mask:0xf bound_ctrl:1
	v_mov_b32_dpp v11, v6 row_shr:2 row_mask:0xf bank_mask:0xf bound_ctrl:1
	v_mov_b32_dpp v12, v212 row_shl:1 row_mask:0xf bank_mask:0xf bound_ctrl:1
	v_cndmask_b32_e64 v10, v10, v12, s[6:7]
	v_cndmask_b32_e64 v12, v11, v212, s[4:5]
	v_mov_b32_dpp v11, v7 row_shr:1 row_mask:0xf bank_mask:0xf bound_ctrl:1
	v_mov_b32_dpp v14, v213 row_shl:1 row_mask:0xf bank_mask:0xf bound_ctrl:1
	v_mov_b32_dpp v13, v7 row_shr:2 row_mask:0xf bank_mask:0xf bound_ctrl:1
; __device__ __forceinline__ unsigned cvt_pk_bf16(float lo, float hi) { const bf16x2_t r = __builtin_convertvector((f32x2){lo, hi}, bf16x2_t); return __builtin_bit_cast(unsigned, r); }
; __device__ __forceinline__ float silu_f(float x) { return x * __builtin_amdgcn_rcpf(1.0f + __expf(-x)); }
; __device__ __forceinline__ unsigned xb_xcc_id() { return (unsigned)__builtin_amdgcn_s_getreg((3 << 11) | 20) & 0xFu; }
;     __device__ __forceinline__ void sample(f32x4 (&acc)[2][2][4][2], const Unit& u, int row0t, int wr, int wc, int fr, int fq) const {
;     ...
;             for (int k = 0; k < 4; ++k) { const int m = mp + k;
;                 const f32x4 uu = conv4s(acc[ai][1][m][n], pv[k], t, w0, w1, w2, bsv);
;                 const f32x4 ua = acc[ai][0][m][n];
;                 u32x2 w; w.x = cvt_pk_bf16(silu_f(ua[0]) * uu[0], silu_f(ua[1]) * uu[1]); w.y = cvt_pk_bf16(silu_f(ua[2]) * uu[2], silu_f(ua[3]) * uu[3]);
;                 if ((step & 1) == 0) pend[m] = w;
;                 else { u32x4 o; if (n == 1) { o.x = pend[m].x; o.y = pend[m].y; o.z = w.x; o.w = w.y; } else { o.x = w.x; o.y = w.y; o.z = pend[m].x; o.w = pend[m].y; }
;                     *(u32x4*)((char*)act + rowoff0 + (unsigned)((ai * HALF + m * 16) * DFF * 2) + (unsigned)(ca * 2)) = o; }
;                 __builtin_amdgcn_sched_barrier(0);
;             }
; __device__ __forceinline__ void xcd_barrier(const XcdBarrier& b) {
;     asm volatile("s_waitcnt vmcnt(0)" ::: "memory");
;     __syncthreads();
;     if (threadIdx.x == 0) {
;         unsigned* bar = b.bar;
;         unsigned bx_ = (unsigned)__builtin_amdgcn_readfirstlane((int)xb_xcc_id()); asm volatile("" : "+s"(bx_));
;         __builtin_amdgcn_s_waitcnt(0);
;         unsigned nloc = b.st[0], nx = b.st[1];
;         if (nloc == 0u) { xcd_barrier_complete(bar, bx_, nloc, nx); b.st[0] = nloc; b.st[1] = nx; }
	v_cndmask_b32_e64 v11, v11, v14, s[6:7]
	v_pk_fma_f32 v[6:7], v[6:7], v[44:45], v[48:49]
	v_cndmask_b32_e64 v13, v13, v213, s[4:5]
	v_pk_fma_f32 v[6:7], v[32:33], v[10:11], v[6:7]
	v_mul_f32_e32 v10, 0xbfb8aa3b, v28
	v_mul_f32_e32 v11, 0xbfb8aa3b, v29
	v_exp_f32_e32 v10, v10
	v_exp_f32_e32 v11, v11
	v_pk_fma_f32 v[6:7], v[20:21], v[12:13], v[6:7]
	v_mul_f32_e32 v12, 0xbfb8aa3b, v30
	v_mul_f32_e32 v13, 0xbfb8aa3b, v31
	s_nop 0
	s_nop 0
	s_nop 0
	v_exp_f32_e32 v12, v12
	v_exp_f32_e32 v13, v13
	v_mov_b32_dpp v14, v8 row_shr:1 row_mask:0xf bank_mask:0xf bound_ctrl:1
	v_mov_b32_dpp v15, v8 row_shr:2 row_mask:0xf bank_mask:0xf bound_ctrl:1
	v_mov_b32_dpp v16, v214 row_shl:1 row_mask:0xf bank_mask:0xf bound_ctrl:1
	v_cndmask_b32_e64 v14, v14, v16, s[6:7]
	v_cndmask_b32_e64 v16, v15, v214, s[4:5]
	s_nop 0
	s_nop 0
	v_add_f32_e32 v10, 1.0, v10
	v_add_f32_e32 v11, 1.0, v11
	v_mov_b32_dpp v15, v9 row_shr:1 row_mask:0xf bank_mask:0xf bound_ctrl:1
	s_nop 0
	v_mov_b32_dpp v18, v215 row_shl:1 row_mask:0xf bank_mask:0xf bound_ctrl:1
	v_rcp_f32_e32 v10, v10
	v_rcp_f32_e32 v11, v11
	v_mov_b32_dpp v17, v9 row_shr:2 row_mask:0xf bank_mask:0xf bound_ctrl:1
	v_cndmask_b32_e64 v15, v15, v18, s[6:7]
	v_pk_fma_f32 v[8:9], v[8:9], v[46:47], v[50:51]
	v_add_f32_e32 v12, 1.0, v12
	v_add_f32_e32 v13, 1.0, v13
	v_cndmask_b32_e64 v17, v17, v215, s[4:5]
	v_pk_fma_f32 v[8:9], v[34:35], v[14:15], v[8:9]
	v_rcp_f32_e32 v12, v12
	v_rcp_f32_e32 v13, v13
	v_pk_fma_f32 v[8:9], v[22:23], v[16:17], v[8:9]
	v_pk_mul_f32 v[10:11], v[28:29], v[10:11]
	s_mov_b32 s0, 0xdc000
	v_pk_mul_f32 v[6:7], v[10:11], v[6:7]
	s_nop 0
	v_cvt_pk_bf16_f32 v64, v6, v7
	v_pk_mul_f32 v[6:7], v[30:31], v[12:13]
	s_nop 0
	v_pk_mul_f32 v[6:7], v[6:7], v[8:9]
	s_nop 0
	v_cvt_pk_bf16_f32 v65, v6, v7
	v_add_co_u32_e32 v6, vcc, s0, v114
	s_nop 1
	v_addc_co_u32_e32 v7, vcc, 0, v115, vcc
	global_store_dwordx4 v[6:7], v[64:67], off
	s_nop 0
	s_nop 0
	s_nop 0
	v_mov_b32_dpp v6, v2 row_shr:1 row_mask:0xf bank_mask:0xf bound_ctrl:1
	v_mov_b32_dpp v7, v2 row_shr:2 row_mask:0xf bank_mask:0xf bound_ctrl:1
	v_mov_b32_dpp v8, v216 row_shl:1 row_mask:0xf bank_mask:0xf bound_ctrl:1
	v_cndmask_b32_e64 v6, v6, v8, s[6:7]
	v_cndmask_b32_e64 v8, v7, v216, s[4:5]
	v_mov_b32_dpp v7, v3 row_shr:1 row_mask:0xf bank_mask:0xf bound_ctrl:1
	v_mov_b32_dpp v10, v217 row_shl:1 row_mask:0xf bank_mask:0xf bound_ctrl:1
	v_mov_b32_dpp v9, v3 row_shr:2 row_mask:0xf bank_mask:0xf bound_ctrl:1
	v_cndmask_b32_e64 v7, v7, v10, s[6:7]
	v_pk_fma_f32 v[2:3], v[2:3], v[44:45], v[48:49]
	v_cndmask_b32_e64 v9, v9, v217, s[4:5]
	v_pk_fma_f32 v[2:3], v[32:33], v[6:7], v[2:3]
	v_mul_f32_e32 v6, 0xbfb8aa3b, v24
	v_mul_f32_e32 v7, 0xbfb8aa3b, v25
	v_exp_f32_e32 v6, v6
	v_exp_f32_e32 v7, v7
	v_pk_fma_f32 v[2:3], v[20:21], v[8:9], v[2:3]
	v_mul_f32_e32 v8, 0xbfb8aa3b, v26
	v_mul_f32_e32 v9, 0xbfb8aa3b, v27
	s_nop 0
	s_nop 0
	s_nop 0
	v_exp_f32_e32 v8, v8
	v_exp_f32_e32 v9, v9
	v_mov_b32_dpp v10, v4 row_shr:1 row_mask:0xf bank_mask:0xf bound_ctrl:1
	v_mov_b32_dpp v11, v4 row_shr:2 row_mask:0xf bank_mask:0xf bound_ctrl:1
	v_mov_b32_dpp v12, v218 row_shl:1 row_mask:0xf bank_mask:0xf bound_ctrl:1
	v_cndmask_b32_e64 v10, v10, v12, s[6:7]
	v_cndmask_b32_e64 v12, v11, v218, s[4:5]
	s_nop 0
	s_nop 0
	v_add_f32_e32 v6, 1.0, v6
	v_add_f32_e32 v7, 1.0, v7
	v_mov_b32_dpp v11, v5 row_shr:1 row_mask:0xf bank_mask:0xf bound_ctrl:1
	s_nop 0
	v_mov_b32_dpp v14, v219 row_shl:1 row_mask:0xf bank_mask:0xf bound_ctrl:1
	v_rcp_f32_e32 v6, v6
	v_rcp_f32_e32 v7, v7
	v_mov_b32_dpp v13, v5 row_shr:2 row_mask:0xf bank_mask:0xf bound_ctrl:1
	v_cndmask_b32_e64 v11, v11, v14, s[6:7]
	v_pk_fma_f32 v[4:5], v[4:5], v[46:47], v[50:51]
	v_add_f32_e32 v8, 1.0, v8
	v_add_f32_e32 v9, 1.0, v9
	v_cndmask_b32_e64 v13, v13, v219, s[4:5]
	v_pk_fma_f32 v[4:5], v[34:35], v[10:11], v[4:5]
	v_rcp_f32_e32 v8, v8
	v_rcp_f32_e32 v9, v9
	v_pk_fma_f32 v[4:5], v[22:23], v[12:13], v[4:5]
	v_pk_mul_f32 v[6:7], v[24:25], v[6:7]
	s_nop 0
	v_pk_mul_f32 v[2:3], v[6:7], v[2:3]
	s_nop 0
	v_cvt_pk_bf16_f32 v54, v2, v3
	v_pk_mul_f32 v[2:3], v[26:27], v[8:9]
	s_nop 0
	v_pk_mul_f32 v[2:3], v[2:3], v[4:5]
	s_nop 0
	v_cvt_pk_bf16_f32 v55, v2, v3
	v_add_co_u32_e32 v2, vcc, 0xf2000, v114
	s_nop 1
	v_addc_co_u32_e32 v3, vcc, 0, v115, vcc
	global_store_dwordx4 v[2:3], v[54:57], off
.LBB0_1377:
	s_waitcnt vmcnt(0)
	s_waitcnt lgkmcnt(0)
	s_barrier
	s_and_saveexec_b64 s[0:1], s[74:75]
	v_readlane_b32 s92, v239, 18
	v_readlane_b32 s93, v239, 19
	v_readlane_b32 s82, v239, 22
	v_readlane_b32 s84, v239, 24
	s_mov_b64 s[94:95], s[78:79]
	v_readlane_b32 s96, v239, 20
	v_readlane_b32 s73, v245, 41
	v_readlane_b32 s77, v245, 42
	v_readlane_b32 s78, v245, 54
	v_readlane_b32 s79, v245, 55
	v_readlane_b32 s83, v239, 23
	v_readlane_b32 s85, v239, 25
	v_readlane_b32 s81, v239, 26
	v_readlane_b32 s93, v239, 27
	v_readlane_b32 s97, v239, 21
	s_cbranch_execz .LBB0_1429
	s_getreg_b32 s2, hwreg(HW_REG_XCC_ID, 0, 4)
	v_readlane_b32 s3, v244, 56
	s_and_b32 s2, s2, 15
	s_waitcnt vmcnt(0) expcnt(0) lgkmcnt(0)
	v_mov_b32_e32 v2, s3
	ds_read_b32 v4, v2
	v_readlane_b32 s3, v244, 57
	s_waitcnt lgkmcnt(0)
	v_cmp_ne_u32_e32 vcc, 0, v4
	v_mov_b32_e32 v2, s3
	ds_read_b32 v2, v2
	s_cbranch_vccnz .LBB0_1393
	s_mov_b32 s3, 1
	s_branch .LBB0_1381
